# gla_prep rewritten by hand: all q/k loads in flight during the gate cumsum, two halves of 32 tokens, bounded outstanding VMEM
# speedup vs baseline: 1.0061x; 1.0061x over previous
.LBB0_219:
	s_cmp_lt_i32 s24, 3
	s_cselect_b64 s[4:5], -1, 0
	s_cmp_gt_i32 s25, 2
	s_cselect_b64 s[6:7], -1, 0
	s_and_b64 s[4:5], s[4:5], s[6:7]
	s_andn2_b64 vcc, exec, s[4:5]
	s_cbranch_vccnz .LBB0_279
	s_cmpk_gt_i32 s2, 0xff
	s_cbranch_scc1 .LBB0_225
	s_mov_b64 exec, -1
	s_load_dwordx16 s[4:19], s[0:1], 0x40
	s_load_dword s3, s[0:1], 0x148
	v_lshlrev_b32_e32 v0, 2, v129
	v_lshlrev_b32_e32 v1, 1, v129
	v_lshlrev_b32_e32 v2, 7, v129
	v_mov_b32_e32 v3, 0
	v_lshrrev_b32_e32 v4, 4, v129
	v_and_b32_e32 v5, 15, v129
	v_mul_u32_u24_e32 v4, 0x1a00, v4
	v_lshl_add_u32 v4, v5, 1, v4
	s_mov_b32 s82, s2
	s_waitcnt lgkmcnt(0)
	s_mov_b32 s7, 0xbfb8aa3b
	s_mov_b32 s9, 0x3f317217
	s_mov_b64 s[84:85], s[12:13]
	s_mov_b64 s[80:81], s[14:15]
.Lprep_item:
	s_barrier
	s_lshr_b32 s4, s82, 5
	s_lshl_b32 s4, s4, 11
	s_and_b32 s5, s82, 31
	s_lshl_b32 s5, s5, 6
	s_add_u32 s4, s4, s5
	s_mul_i32 s5, s4, 0x1a00
	s_mul_hi_u32 s6, s4, 0x1a00
	s_add_u32 s20, s46, s5
	s_addc_u32 s21, s47, s6
	s_mov_b64 s[22:23], s[20:21]
	s_add_u32 s30, s20, 0x1800
	s_addc_u32 s31, s21, 0
	s_add_u32 s16, s30, 0x34000
	s_addc_u32 s17, s31, 0
	s_lshl_b32 s5, s82, 16
	s_lshr_b32 s6, s82, 16
	s_add_u32 s26, s46, 0x6b40000
	s_addc_u32 s27, s47, 0
	s_add_u32 s26, s26, s5
	s_addc_u32 s27, s27, s6
	s_mul_i32 s5, s82, 0x1800
	s_add_u32 s28, s46, 0x7b40000
	s_addc_u32 s29, s47, 0
	s_add_u32 s28, s28, s5
	s_addc_u32 s29, s29, 0
	s_mov_b64 s[34:35], s[84:85]
	global_load_ushort v6, v4, s[30:31]
	global_load_ushort v7, v4, s[16:17]
	global_load_dword v16, v0, s[34:35]
	global_load_dword v17, v0, s[34:35] offset:2048
	s_add_u32 s34, s34, 0x1000
	s_addc_u32 s35, s35, 0
	global_load_dword v18, v0, s[34:35]
	global_load_dword v19, v0, s[34:35] offset:2048
	s_add_u32 s34, s34, 0x1000
	s_addc_u32 s35, s35, 0
	global_load_dword v20, v0, s[34:35]
	global_load_dword v21, v0, s[34:35] offset:2048
	s_add_u32 s34, s34, 0x1000
	s_addc_u32 s35, s35, 0
	global_load_dword v22, v0, s[34:35]
	global_load_dword v23, v0, s[34:35] offset:2048
	s_add_u32 s34, s34, 0x1000
	s_addc_u32 s35, s35, 0
	global_load_dword v24, v0, s[34:35]
	global_load_dword v25, v0, s[34:35] offset:2048
	s_add_u32 s34, s34, 0x1000
	s_addc_u32 s35, s35, 0
	global_load_dword v26, v0, s[34:35]
	global_load_dword v27, v0, s[34:35] offset:2048
	s_add_u32 s34, s34, 0x1000
	s_addc_u32 s35, s35, 0
	global_load_dword v28, v0, s[34:35]
	global_load_dword v29, v0, s[34:35] offset:2048
	s_add_u32 s34, s34, 0x1000
	s_addc_u32 s35, s35, 0
	global_load_dword v30, v0, s[34:35]
	global_load_dword v31, v0, s[34:35] offset:2048
	global_load_dword v32, v0, s[80:81]
	s_waitcnt vmcnt(17)
	v_lshlrev_b32_e32 v6, 16, v6
	v_lshlrev_b32_e32 v7, 16, v7
	ds_write_b32 v0, v6
	ds_write_b32 v0, v7 offset:2048
	s_waitcnt lgkmcnt(0)
	s_barrier
	ds_read_b128 v[34:37], v3 offset:0
	ds_read_b128 v[38:41], v3 offset:16
	ds_read_b128 v[42:45], v3 offset:32
	ds_read_b128 v[46:49], v3 offset:48
	ds_read_b128 v[200:203], v3 offset:64
	ds_read_b128 v[204:207], v3 offset:80
	ds_read_b128 v[208:211], v3 offset:96
	ds_read_b128 v[212:215], v3 offset:112
	s_waitcnt vmcnt(0)
	s_waitcnt lgkmcnt(0)
	ds_read_b128 v[216:219], v3 offset:128
	ds_read_b128 v[220:223], v3 offset:144
	ds_read_b128 v[224:227], v3 offset:160
	ds_read_b128 v[232:235], v3 offset:176
	ds_read_b128 v[236:239], v3 offset:192
	ds_read_b128 v[240:243], v3 offset:208
	ds_read_b128 v[244:247], v3 offset:224
	ds_read_b128 v[248:251], v3 offset:240
	global_load_ushort v136, v1, s[20:21]
	global_load_ushort v137, v1, s[20:21] offset:1024
	s_add_u32 s20, s20, 0x1a00
	s_addc_u32 s21, s21, 0
	global_load_ushort v138, v1, s[20:21]
	global_load_ushort v139, v1, s[20:21] offset:1024
	s_add_u32 s20, s20, 0x1a00
	s_addc_u32 s21, s21, 0
	v_fma_f32 v50, v16, v34, v32
	v_fma_f32 v51, v16, v200, v32
	v_fmac_f32_e32 v50, v17, v35
	v_fmac_f32_e32 v51, v17, v201
	v_fmac_f32_e32 v50, v18, v36
	v_fmac_f32_e32 v51, v18, v202
	v_fmac_f32_e32 v50, v19, v37
	v_fmac_f32_e32 v51, v19, v203
	v_fmac_f32_e32 v50, v20, v38
	v_fmac_f32_e32 v51, v20, v204
	v_fmac_f32_e32 v50, v21, v39
	v_fmac_f32_e32 v51, v21, v205
	v_fmac_f32_e32 v50, v22, v40
	v_fmac_f32_e32 v51, v22, v206
	v_fmac_f32_e32 v50, v23, v41
	v_fmac_f32_e32 v51, v23, v207
	v_fmac_f32_e32 v50, v24, v42
	v_fmac_f32_e32 v51, v24, v208
	v_fmac_f32_e32 v50, v25, v43
	v_fmac_f32_e32 v51, v25, v209
	v_fmac_f32_e32 v50, v26, v44
	v_fmac_f32_e32 v51, v26, v210
	v_fmac_f32_e32 v50, v27, v45
	v_fmac_f32_e32 v51, v27, v211
	v_fmac_f32_e32 v50, v28, v46
	v_fmac_f32_e32 v51, v28, v212
	v_fmac_f32_e32 v50, v29, v47
	v_fmac_f32_e32 v51, v29, v213
	v_fmac_f32_e32 v50, v30, v48
	v_fmac_f32_e32 v51, v30, v214
	v_fmac_f32_e32 v50, v31, v49
	v_fmac_f32_e32 v51, v31, v215
	v_mul_f32_e64 v52, |v50|, s7
	v_mul_f32_e64 v53, |v51|, s7
	v_exp_f32_e32 v52, v52
	v_exp_f32_e32 v53, v53
	v_min_f32_e32 v50, 0, v50
	v_add_f32_e32 v52, 1.0, v52
	v_add_f32_e32 v53, 1.0, v53
	v_log_f32_e32 v52, v52
	v_log_f32_e32 v53, v53
	v_min_f32_e32 v51, 0, v51
	v_mul_f32_e32 v54, 0x3f317217, v52
	v_mul_f32_e32 v55, 0x3f317217, v53
	v_fma_f32 v56, v52, s9, -v54
	v_fma_f32 v57, v53, s9, -v55
	v_fmac_f32_e32 v56, 0x3377d1cf, v52
	v_fmac_f32_e32 v57, 0x3377d1cf, v53
	v_add_f32_e32 v54, v54, v56
	v_add_f32_e32 v55, v55, v57
	v_sub_f32_e32 v50, v50, v54
	v_sub_f32_e32 v51, v51, v55
	v_mul_f32_e32 v64, 0x3d800000, v50
	v_fmamk_f32 v65, v51, 0x3d800000, v64
	s_waitcnt lgkmcnt(0)
	ds_read_b128 v[34:37], v3 offset:256
	ds_read_b128 v[38:41], v3 offset:272
	ds_read_b128 v[42:45], v3 offset:288
	ds_read_b128 v[46:49], v3 offset:304
	ds_read_b128 v[200:203], v3 offset:320
	ds_read_b128 v[204:207], v3 offset:336
	ds_read_b128 v[208:211], v3 offset:352
	ds_read_b128 v[212:215], v3 offset:368
	global_load_ushort v140, v1, s[20:21]
	global_load_ushort v141, v1, s[20:21] offset:1024
	s_add_u32 s20, s20, 0x1a00
	s_addc_u32 s21, s21, 0
	global_load_ushort v142, v1, s[20:21]
	global_load_ushort v143, v1, s[20:21] offset:1024
	s_add_u32 s20, s20, 0x1a00
	s_addc_u32 s21, s21, 0
	v_fma_f32 v50, v16, v216, v32
	v_fma_f32 v51, v16, v236, v32
	v_fmac_f32_e32 v50, v17, v217
	v_fmac_f32_e32 v51, v17, v237
	v_fmac_f32_e32 v50, v18, v218
	v_fmac_f32_e32 v51, v18, v238
	v_fmac_f32_e32 v50, v19, v219
	v_fmac_f32_e32 v51, v19, v239
	v_fmac_f32_e32 v50, v20, v220
	v_fmac_f32_e32 v51, v20, v240
	v_fmac_f32_e32 v50, v21, v221
	v_fmac_f32_e32 v51, v21, v241
	v_fmac_f32_e32 v50, v22, v222
	v_fmac_f32_e32 v51, v22, v242
	v_fmac_f32_e32 v50, v23, v223
	v_fmac_f32_e32 v51, v23, v243
	v_fmac_f32_e32 v50, v24, v224
	v_fmac_f32_e32 v51, v24, v244
	v_fmac_f32_e32 v50, v25, v225
	v_fmac_f32_e32 v51, v25, v245
	v_fmac_f32_e32 v50, v26, v226
	v_fmac_f32_e32 v51, v26, v246
	v_fmac_f32_e32 v50, v27, v227
	v_fmac_f32_e32 v51, v27, v247
	v_fmac_f32_e32 v50, v28, v232
	v_fmac_f32_e32 v51, v28, v248
	v_fmac_f32_e32 v50, v29, v233
	v_fmac_f32_e32 v51, v29, v249
	v_fmac_f32_e32 v50, v30, v234
	v_fmac_f32_e32 v51, v30, v250
	v_fmac_f32_e32 v50, v31, v235
	v_fmac_f32_e32 v51, v31, v251
	v_mul_f32_e64 v52, |v50|, s7
	v_mul_f32_e64 v53, |v51|, s7
	v_exp_f32_e32 v52, v52
	v_exp_f32_e32 v53, v53
	v_min_f32_e32 v50, 0, v50
	v_add_f32_e32 v52, 1.0, v52
	v_add_f32_e32 v53, 1.0, v53
	v_log_f32_e32 v52, v52
	v_log_f32_e32 v53, v53
	v_min_f32_e32 v51, 0, v51
	v_mul_f32_e32 v54, 0x3f317217, v52
	v_mul_f32_e32 v55, 0x3f317217, v53
	v_fma_f32 v56, v52, s9, -v54
	v_fma_f32 v57, v53, s9, -v55
	v_fmac_f32_e32 v56, 0x3377d1cf, v52
	v_fmac_f32_e32 v57, 0x3377d1cf, v53
	v_add_f32_e32 v54, v54, v56
	v_add_f32_e32 v55, v55, v57
	v_sub_f32_e32 v50, v50, v54
	v_sub_f32_e32 v51, v51, v55
	v_fmamk_f32 v66, v50, 0x3d800000, v65
	v_fmamk_f32 v67, v51, 0x3d800000, v66
	s_waitcnt lgkmcnt(0)
	ds_read_b128 v[216:219], v3 offset:384
	ds_read_b128 v[220:223], v3 offset:400
	ds_read_b128 v[224:227], v3 offset:416
	ds_read_b128 v[232:235], v3 offset:432
	ds_read_b128 v[236:239], v3 offset:448
	ds_read_b128 v[240:243], v3 offset:464
	ds_read_b128 v[244:247], v3 offset:480
	ds_read_b128 v[248:251], v3 offset:496
	global_load_ushort v144, v1, s[20:21]
	global_load_ushort v145, v1, s[20:21] offset:1024
	s_add_u32 s20, s20, 0x1a00
	s_addc_u32 s21, s21, 0
	global_load_ushort v146, v1, s[20:21]
	global_load_ushort v147, v1, s[20:21] offset:1024
	s_add_u32 s20, s20, 0x1a00
	s_addc_u32 s21, s21, 0
	v_fma_f32 v50, v16, v34, v32
	v_fma_f32 v51, v16, v200, v32
	v_fmac_f32_e32 v50, v17, v35
	v_fmac_f32_e32 v51, v17, v201
	v_fmac_f32_e32 v50, v18, v36
	v_fmac_f32_e32 v51, v18, v202
	v_fmac_f32_e32 v50, v19, v37
	v_fmac_f32_e32 v51, v19, v203
	v_fmac_f32_e32 v50, v20, v38
	v_fmac_f32_e32 v51, v20, v204
	v_fmac_f32_e32 v50, v21, v39
	v_fmac_f32_e32 v51, v21, v205
	v_fmac_f32_e32 v50, v22, v40
	v_fmac_f32_e32 v51, v22, v206
	v_fmac_f32_e32 v50, v23, v41
	v_fmac_f32_e32 v51, v23, v207
	v_fmac_f32_e32 v50, v24, v42
	v_fmac_f32_e32 v51, v24, v208
	v_fmac_f32_e32 v50, v25, v43
	v_fmac_f32_e32 v51, v25, v209
	v_fmac_f32_e32 v50, v26, v44
	v_fmac_f32_e32 v51, v26, v210
	v_fmac_f32_e32 v50, v27, v45
	v_fmac_f32_e32 v51, v27, v211
	v_fmac_f32_e32 v50, v28, v46
	v_fmac_f32_e32 v51, v28, v212
	v_fmac_f32_e32 v50, v29, v47
	v_fmac_f32_e32 v51, v29, v213
	v_fmac_f32_e32 v50, v30, v48
	v_fmac_f32_e32 v51, v30, v214
	v_fmac_f32_e32 v50, v31, v49
	v_fmac_f32_e32 v51, v31, v215
	v_mul_f32_e64 v52, |v50|, s7
	v_mul_f32_e64 v53, |v51|, s7
	v_exp_f32_e32 v52, v52
	v_exp_f32_e32 v53, v53
	v_min_f32_e32 v50, 0, v50
	v_add_f32_e32 v52, 1.0, v52
	v_add_f32_e32 v53, 1.0, v53
	v_log_f32_e32 v52, v52
	v_log_f32_e32 v53, v53
	v_min_f32_e32 v51, 0, v51
	v_mul_f32_e32 v54, 0x3f317217, v52
	v_mul_f32_e32 v55, 0x3f317217, v53
	v_fma_f32 v56, v52, s9, -v54
	v_fma_f32 v57, v53, s9, -v55
	v_fmac_f32_e32 v56, 0x3377d1cf, v52
	v_fmac_f32_e32 v57, 0x3377d1cf, v53
	v_add_f32_e32 v54, v54, v56
	v_add_f32_e32 v55, v55, v57
	v_sub_f32_e32 v50, v50, v54
	v_sub_f32_e32 v51, v51, v55
	v_fmamk_f32 v68, v50, 0x3d800000, v67
	v_fmamk_f32 v69, v51, 0x3d800000, v68
	s_waitcnt lgkmcnt(0)
	ds_read_b128 v[34:37], v3 offset:512
	ds_read_b128 v[38:41], v3 offset:528
	ds_read_b128 v[42:45], v3 offset:544
	ds_read_b128 v[46:49], v3 offset:560
	ds_read_b128 v[200:203], v3 offset:576
	ds_read_b128 v[204:207], v3 offset:592
	ds_read_b128 v[208:211], v3 offset:608
	ds_read_b128 v[212:215], v3 offset:624
	global_load_ushort v148, v1, s[20:21]
	global_load_ushort v149, v1, s[20:21] offset:1024
	s_add_u32 s20, s20, 0x1a00
	s_addc_u32 s21, s21, 0
	global_load_ushort v150, v1, s[20:21]
	global_load_ushort v151, v1, s[20:21] offset:1024
	s_add_u32 s20, s20, 0x1a00
	s_addc_u32 s21, s21, 0
	v_fma_f32 v50, v16, v216, v32
	v_fma_f32 v51, v16, v236, v32
	v_fmac_f32_e32 v50, v17, v217
	v_fmac_f32_e32 v51, v17, v237
	v_fmac_f32_e32 v50, v18, v218
	v_fmac_f32_e32 v51, v18, v238
	v_fmac_f32_e32 v50, v19, v219
	v_fmac_f32_e32 v51, v19, v239
	v_fmac_f32_e32 v50, v20, v220
	v_fmac_f32_e32 v51, v20, v240
	v_fmac_f32_e32 v50, v21, v221
	v_fmac_f32_e32 v51, v21, v241
	v_fmac_f32_e32 v50, v22, v222
	v_fmac_f32_e32 v51, v22, v242
	v_fmac_f32_e32 v50, v23, v223
	v_fmac_f32_e32 v51, v23, v243
	v_fmac_f32_e32 v50, v24, v224
	v_fmac_f32_e32 v51, v24, v244
	v_fmac_f32_e32 v50, v25, v225
	v_fmac_f32_e32 v51, v25, v245
	v_fmac_f32_e32 v50, v26, v226
	v_fmac_f32_e32 v51, v26, v246
	v_fmac_f32_e32 v50, v27, v227
	v_fmac_f32_e32 v51, v27, v247
	v_fmac_f32_e32 v50, v28, v232
	v_fmac_f32_e32 v51, v28, v248
	v_fmac_f32_e32 v50, v29, v233
	v_fmac_f32_e32 v51, v29, v249
	v_fmac_f32_e32 v50, v30, v234
	v_fmac_f32_e32 v51, v30, v250
	v_fmac_f32_e32 v50, v31, v235
	v_fmac_f32_e32 v51, v31, v251
	v_mul_f32_e64 v52, |v50|, s7
	v_mul_f32_e64 v53, |v51|, s7
	v_exp_f32_e32 v52, v52
	v_exp_f32_e32 v53, v53
	v_min_f32_e32 v50, 0, v50
	v_add_f32_e32 v52, 1.0, v52
	v_add_f32_e32 v53, 1.0, v53
	v_log_f32_e32 v52, v52
	v_log_f32_e32 v53, v53
	v_min_f32_e32 v51, 0, v51
	v_mul_f32_e32 v54, 0x3f317217, v52
	v_mul_f32_e32 v55, 0x3f317217, v53
	v_fma_f32 v56, v52, s9, -v54
	v_fma_f32 v57, v53, s9, -v55
	v_fmac_f32_e32 v56, 0x3377d1cf, v52
	v_fmac_f32_e32 v57, 0x3377d1cf, v53
	v_add_f32_e32 v54, v54, v56
	v_add_f32_e32 v55, v55, v57
	v_sub_f32_e32 v50, v50, v54
	v_sub_f32_e32 v51, v51, v55
	v_fmamk_f32 v70, v50, 0x3d800000, v69
	v_fmamk_f32 v71, v51, 0x3d800000, v70
	s_waitcnt lgkmcnt(0)
	ds_read_b128 v[216:219], v3 offset:640
	ds_read_b128 v[220:223], v3 offset:656
	ds_read_b128 v[224:227], v3 offset:672
	ds_read_b128 v[232:235], v3 offset:688
	ds_read_b128 v[236:239], v3 offset:704
	ds_read_b128 v[240:243], v3 offset:720
	ds_read_b128 v[244:247], v3 offset:736
	ds_read_b128 v[248:251], v3 offset:752
	global_load_ushort v152, v1, s[20:21]
	global_load_ushort v153, v1, s[20:21] offset:1024
	s_add_u32 s20, s20, 0x1a00
	s_addc_u32 s21, s21, 0
	global_load_ushort v154, v1, s[20:21]
	global_load_ushort v155, v1, s[20:21] offset:1024
	s_add_u32 s20, s20, 0x1a00
	s_addc_u32 s21, s21, 0
	v_fma_f32 v50, v16, v34, v32
	v_fma_f32 v51, v16, v200, v32
	v_fmac_f32_e32 v50, v17, v35
	v_fmac_f32_e32 v51, v17, v201
	v_fmac_f32_e32 v50, v18, v36
	v_fmac_f32_e32 v51, v18, v202
	v_fmac_f32_e32 v50, v19, v37
	v_fmac_f32_e32 v51, v19, v203
	v_fmac_f32_e32 v50, v20, v38
	v_fmac_f32_e32 v51, v20, v204
	v_fmac_f32_e32 v50, v21, v39
	v_fmac_f32_e32 v51, v21, v205
	v_fmac_f32_e32 v50, v22, v40
	v_fmac_f32_e32 v51, v22, v206
	v_fmac_f32_e32 v50, v23, v41
	v_fmac_f32_e32 v51, v23, v207
	v_fmac_f32_e32 v50, v24, v42
	v_fmac_f32_e32 v51, v24, v208
	v_fmac_f32_e32 v50, v25, v43
	v_fmac_f32_e32 v51, v25, v209
	v_fmac_f32_e32 v50, v26, v44
	v_fmac_f32_e32 v51, v26, v210
	v_fmac_f32_e32 v50, v27, v45
	v_fmac_f32_e32 v51, v27, v211
	v_fmac_f32_e32 v50, v28, v46
	v_fmac_f32_e32 v51, v28, v212
	v_fmac_f32_e32 v50, v29, v47
	v_fmac_f32_e32 v51, v29, v213
	v_fmac_f32_e32 v50, v30, v48
	v_fmac_f32_e32 v51, v30, v214
	v_fmac_f32_e32 v50, v31, v49
	v_fmac_f32_e32 v51, v31, v215
	v_mul_f32_e64 v52, |v50|, s7
	v_mul_f32_e64 v53, |v51|, s7
	v_exp_f32_e32 v52, v52
	v_exp_f32_e32 v53, v53
	v_min_f32_e32 v50, 0, v50
	v_add_f32_e32 v52, 1.0, v52
	v_add_f32_e32 v53, 1.0, v53
	v_log_f32_e32 v52, v52
	v_log_f32_e32 v53, v53
	v_min_f32_e32 v51, 0, v51
	v_mul_f32_e32 v54, 0x3f317217, v52
	v_mul_f32_e32 v55, 0x3f317217, v53
	v_fma_f32 v56, v52, s9, -v54
	v_fma_f32 v57, v53, s9, -v55
	v_fmac_f32_e32 v56, 0x3377d1cf, v52
	v_fmac_f32_e32 v57, 0x3377d1cf, v53
	v_add_f32_e32 v54, v54, v56
	v_add_f32_e32 v55, v55, v57
	v_sub_f32_e32 v50, v50, v54
	v_sub_f32_e32 v51, v51, v55
	v_fmamk_f32 v72, v50, 0x3d800000, v71
	v_fmamk_f32 v73, v51, 0x3d800000, v72
	s_waitcnt lgkmcnt(0)
	ds_read_b128 v[34:37], v3 offset:768
	ds_read_b128 v[38:41], v3 offset:784
	ds_read_b128 v[42:45], v3 offset:800
	ds_read_b128 v[46:49], v3 offset:816
	ds_read_b128 v[200:203], v3 offset:832
	ds_read_b128 v[204:207], v3 offset:848
	ds_read_b128 v[208:211], v3 offset:864
	ds_read_b128 v[212:215], v3 offset:880
	global_load_ushort v156, v1, s[20:21]
	global_load_ushort v157, v1, s[20:21] offset:1024
	s_add_u32 s20, s20, 0x1a00
	s_addc_u32 s21, s21, 0
	global_load_ushort v158, v1, s[20:21]
	global_load_ushort v159, v1, s[20:21] offset:1024
	s_add_u32 s20, s20, 0x1a00
	s_addc_u32 s21, s21, 0
	v_fma_f32 v50, v16, v216, v32
	v_fma_f32 v51, v16, v236, v32
	v_fmac_f32_e32 v50, v17, v217
	v_fmac_f32_e32 v51, v17, v237
	v_fmac_f32_e32 v50, v18, v218
	v_fmac_f32_e32 v51, v18, v238
	v_fmac_f32_e32 v50, v19, v219
	v_fmac_f32_e32 v51, v19, v239
	v_fmac_f32_e32 v50, v20, v220
	v_fmac_f32_e32 v51, v20, v240
	v_fmac_f32_e32 v50, v21, v221
	v_fmac_f32_e32 v51, v21, v241
	v_fmac_f32_e32 v50, v22, v222
	v_fmac_f32_e32 v51, v22, v242
	v_fmac_f32_e32 v50, v23, v223
	v_fmac_f32_e32 v51, v23, v243
	v_fmac_f32_e32 v50, v24, v224
	v_fmac_f32_e32 v51, v24, v244
	v_fmac_f32_e32 v50, v25, v225
	v_fmac_f32_e32 v51, v25, v245
	v_fmac_f32_e32 v50, v26, v226
	v_fmac_f32_e32 v51, v26, v246
	v_fmac_f32_e32 v50, v27, v227
	v_fmac_f32_e32 v51, v27, v247
	v_fmac_f32_e32 v50, v28, v232
	v_fmac_f32_e32 v51, v28, v248
	v_fmac_f32_e32 v50, v29, v233
	v_fmac_f32_e32 v51, v29, v249
	v_fmac_f32_e32 v50, v30, v234
	v_fmac_f32_e32 v51, v30, v250
	v_fmac_f32_e32 v50, v31, v235
	v_fmac_f32_e32 v51, v31, v251
	v_mul_f32_e64 v52, |v50|, s7
	v_mul_f32_e64 v53, |v51|, s7
	v_exp_f32_e32 v52, v52
	v_exp_f32_e32 v53, v53
	v_min_f32_e32 v50, 0, v50
	v_add_f32_e32 v52, 1.0, v52
	v_add_f32_e32 v53, 1.0, v53
	v_log_f32_e32 v52, v52
	v_log_f32_e32 v53, v53
	v_min_f32_e32 v51, 0, v51
	v_mul_f32_e32 v54, 0x3f317217, v52
	v_mul_f32_e32 v55, 0x3f317217, v53
	v_fma_f32 v56, v52, s9, -v54
	v_fma_f32 v57, v53, s9, -v55
	v_fmac_f32_e32 v56, 0x3377d1cf, v52
	v_fmac_f32_e32 v57, 0x3377d1cf, v53
	v_add_f32_e32 v54, v54, v56
	v_add_f32_e32 v55, v55, v57
	v_sub_f32_e32 v50, v50, v54
	v_sub_f32_e32 v51, v51, v55
	v_fmamk_f32 v74, v50, 0x3d800000, v73
	v_fmamk_f32 v75, v51, 0x3d800000, v74
	s_waitcnt lgkmcnt(0)
	ds_read_b128 v[216:219], v3 offset:896
	ds_read_b128 v[220:223], v3 offset:912
	ds_read_b128 v[224:227], v3 offset:928
	ds_read_b128 v[232:235], v3 offset:944
	ds_read_b128 v[236:239], v3 offset:960
	ds_read_b128 v[240:243], v3 offset:976
	ds_read_b128 v[244:247], v3 offset:992
	ds_read_b128 v[248:251], v3 offset:1008
	global_load_ushort v160, v1, s[20:21]
	global_load_ushort v161, v1, s[20:21] offset:1024
	s_add_u32 s20, s20, 0x1a00
	s_addc_u32 s21, s21, 0
	global_load_ushort v162, v1, s[20:21]
	global_load_ushort v163, v1, s[20:21] offset:1024
	s_add_u32 s20, s20, 0x1a00
	s_addc_u32 s21, s21, 0
	v_fma_f32 v50, v16, v34, v32
	v_fma_f32 v51, v16, v200, v32
	v_fmac_f32_e32 v50, v17, v35
	v_fmac_f32_e32 v51, v17, v201
	v_fmac_f32_e32 v50, v18, v36
	v_fmac_f32_e32 v51, v18, v202
	v_fmac_f32_e32 v50, v19, v37
	v_fmac_f32_e32 v51, v19, v203
	v_fmac_f32_e32 v50, v20, v38
	v_fmac_f32_e32 v51, v20, v204
	v_fmac_f32_e32 v50, v21, v39
	v_fmac_f32_e32 v51, v21, v205
	v_fmac_f32_e32 v50, v22, v40
	v_fmac_f32_e32 v51, v22, v206
	v_fmac_f32_e32 v50, v23, v41
	v_fmac_f32_e32 v51, v23, v207
	v_fmac_f32_e32 v50, v24, v42
	v_fmac_f32_e32 v51, v24, v208
	v_fmac_f32_e32 v50, v25, v43
	v_fmac_f32_e32 v51, v25, v209
	v_fmac_f32_e32 v50, v26, v44
	v_fmac_f32_e32 v51, v26, v210
	v_fmac_f32_e32 v50, v27, v45
	v_fmac_f32_e32 v51, v27, v211
	v_fmac_f32_e32 v50, v28, v46
	v_fmac_f32_e32 v51, v28, v212
	v_fmac_f32_e32 v50, v29, v47
	v_fmac_f32_e32 v51, v29, v213
	v_fmac_f32_e32 v50, v30, v48
	v_fmac_f32_e32 v51, v30, v214
	v_fmac_f32_e32 v50, v31, v49
	v_fmac_f32_e32 v51, v31, v215
	v_mul_f32_e64 v52, |v50|, s7
	v_mul_f32_e64 v53, |v51|, s7
	v_exp_f32_e32 v52, v52
	v_exp_f32_e32 v53, v53
	v_min_f32_e32 v50, 0, v50
	v_add_f32_e32 v52, 1.0, v52
	v_add_f32_e32 v53, 1.0, v53
	v_log_f32_e32 v52, v52
	v_log_f32_e32 v53, v53
	v_min_f32_e32 v51, 0, v51
	v_mul_f32_e32 v54, 0x3f317217, v52
	v_mul_f32_e32 v55, 0x3f317217, v53
	v_fma_f32 v56, v52, s9, -v54
	v_fma_f32 v57, v53, s9, -v55
	v_fmac_f32_e32 v56, 0x3377d1cf, v52
	v_fmac_f32_e32 v57, 0x3377d1cf, v53
	v_add_f32_e32 v54, v54, v56
	v_add_f32_e32 v55, v55, v57
	v_sub_f32_e32 v50, v50, v54
	v_sub_f32_e32 v51, v51, v55
	v_fmamk_f32 v76, v50, 0x3d800000, v75
	v_fmamk_f32 v77, v51, 0x3d800000, v76
	s_waitcnt lgkmcnt(0)
	ds_read_b128 v[34:37], v3 offset:1024
	ds_read_b128 v[38:41], v3 offset:1040
	ds_read_b128 v[42:45], v3 offset:1056
	ds_read_b128 v[46:49], v3 offset:1072
	ds_read_b128 v[200:203], v3 offset:1088
	ds_read_b128 v[204:207], v3 offset:1104
	ds_read_b128 v[208:211], v3 offset:1120
	ds_read_b128 v[212:215], v3 offset:1136
	global_load_ushort v164, v1, s[20:21]
	global_load_ushort v165, v1, s[20:21] offset:1024
	s_add_u32 s20, s20, 0x1a00
	s_addc_u32 s21, s21, 0
	global_load_ushort v166, v1, s[20:21]
	global_load_ushort v167, v1, s[20:21] offset:1024
	s_add_u32 s20, s20, 0x1a00
	s_addc_u32 s21, s21, 0
	v_fma_f32 v50, v16, v216, v32
	v_fma_f32 v51, v16, v236, v32
	v_fmac_f32_e32 v50, v17, v217
	v_fmac_f32_e32 v51, v17, v237
	v_fmac_f32_e32 v50, v18, v218
	v_fmac_f32_e32 v51, v18, v238
	v_fmac_f32_e32 v50, v19, v219
	v_fmac_f32_e32 v51, v19, v239
	v_fmac_f32_e32 v50, v20, v220
	v_fmac_f32_e32 v51, v20, v240
	v_fmac_f32_e32 v50, v21, v221
	v_fmac_f32_e32 v51, v21, v241
	v_fmac_f32_e32 v50, v22, v222
	v_fmac_f32_e32 v51, v22, v242
	v_fmac_f32_e32 v50, v23, v223
	v_fmac_f32_e32 v51, v23, v243
	v_fmac_f32_e32 v50, v24, v224
	v_fmac_f32_e32 v51, v24, v244
	v_fmac_f32_e32 v50, v25, v225
	v_fmac_f32_e32 v51, v25, v245
	v_fmac_f32_e32 v50, v26, v226
	v_fmac_f32_e32 v51, v26, v246
	v_fmac_f32_e32 v50, v27, v227
	v_fmac_f32_e32 v51, v27, v247
	v_fmac_f32_e32 v50, v28, v232
	v_fmac_f32_e32 v51, v28, v248
	v_fmac_f32_e32 v50, v29, v233
	v_fmac_f32_e32 v51, v29, v249
	v_fmac_f32_e32 v50, v30, v234
	v_fmac_f32_e32 v51, v30, v250
	v_fmac_f32_e32 v50, v31, v235
	v_fmac_f32_e32 v51, v31, v251
	v_mul_f32_e64 v52, |v50|, s7
	v_mul_f32_e64 v53, |v51|, s7
	v_exp_f32_e32 v52, v52
	v_exp_f32_e32 v53, v53
	v_min_f32_e32 v50, 0, v50
	v_add_f32_e32 v52, 1.0, v52
	v_add_f32_e32 v53, 1.0, v53
	v_log_f32_e32 v52, v52
	v_log_f32_e32 v53, v53
	v_min_f32_e32 v51, 0, v51
	v_mul_f32_e32 v54, 0x3f317217, v52
	v_mul_f32_e32 v55, 0x3f317217, v53
	v_fma_f32 v56, v52, s9, -v54
	v_fma_f32 v57, v53, s9, -v55
	v_fmac_f32_e32 v56, 0x3377d1cf, v52
	v_fmac_f32_e32 v57, 0x3377d1cf, v53
	v_add_f32_e32 v54, v54, v56
	v_add_f32_e32 v55, v55, v57
	v_sub_f32_e32 v50, v50, v54
	v_sub_f32_e32 v51, v51, v55
	v_fmamk_f32 v78, v50, 0x3d800000, v77
	v_fmamk_f32 v79, v51, 0x3d800000, v78
	s_waitcnt lgkmcnt(0)
	ds_read_b128 v[216:219], v3 offset:1152
	ds_read_b128 v[220:223], v3 offset:1168
	ds_read_b128 v[224:227], v3 offset:1184
	ds_read_b128 v[232:235], v3 offset:1200
	ds_read_b128 v[236:239], v3 offset:1216
	ds_read_b128 v[240:243], v3 offset:1232
	ds_read_b128 v[244:247], v3 offset:1248
	ds_read_b128 v[248:251], v3 offset:1264
	global_load_ushort v168, v1, s[20:21]
	global_load_ushort v169, v1, s[20:21] offset:1024
	s_add_u32 s20, s20, 0x1a00
	s_addc_u32 s21, s21, 0
	global_load_ushort v170, v1, s[20:21]
	global_load_ushort v171, v1, s[20:21] offset:1024
	s_add_u32 s20, s20, 0x1a00
	s_addc_u32 s21, s21, 0
	v_fma_f32 v50, v16, v34, v32
	v_fma_f32 v51, v16, v200, v32
	v_fmac_f32_e32 v50, v17, v35
	v_fmac_f32_e32 v51, v17, v201
	v_fmac_f32_e32 v50, v18, v36
	v_fmac_f32_e32 v51, v18, v202
	v_fmac_f32_e32 v50, v19, v37
	v_fmac_f32_e32 v51, v19, v203
	v_fmac_f32_e32 v50, v20, v38
	v_fmac_f32_e32 v51, v20, v204
	v_fmac_f32_e32 v50, v21, v39
	v_fmac_f32_e32 v51, v21, v205
	v_fmac_f32_e32 v50, v22, v40
	v_fmac_f32_e32 v51, v22, v206
	v_fmac_f32_e32 v50, v23, v41
	v_fmac_f32_e32 v51, v23, v207
	v_fmac_f32_e32 v50, v24, v42
	v_fmac_f32_e32 v51, v24, v208
	v_fmac_f32_e32 v50, v25, v43
	v_fmac_f32_e32 v51, v25, v209
	v_fmac_f32_e32 v50, v26, v44
	v_fmac_f32_e32 v51, v26, v210
	v_fmac_f32_e32 v50, v27, v45
	v_fmac_f32_e32 v51, v27, v211
	v_fmac_f32_e32 v50, v28, v46
	v_fmac_f32_e32 v51, v28, v212
	v_fmac_f32_e32 v50, v29, v47
	v_fmac_f32_e32 v51, v29, v213
	v_fmac_f32_e32 v50, v30, v48
	v_fmac_f32_e32 v51, v30, v214
	v_fmac_f32_e32 v50, v31, v49
	v_fmac_f32_e32 v51, v31, v215
	v_mul_f32_e64 v52, |v50|, s7
	v_mul_f32_e64 v53, |v51|, s7
	v_exp_f32_e32 v52, v52
	v_exp_f32_e32 v53, v53
	v_min_f32_e32 v50, 0, v50
	v_add_f32_e32 v52, 1.0, v52
	v_add_f32_e32 v53, 1.0, v53
	v_log_f32_e32 v52, v52
	v_log_f32_e32 v53, v53
	v_min_f32_e32 v51, 0, v51
	v_mul_f32_e32 v54, 0x3f317217, v52
	v_mul_f32_e32 v55, 0x3f317217, v53
	v_fma_f32 v56, v52, s9, -v54
	v_fma_f32 v57, v53, s9, -v55
	v_fmac_f32_e32 v56, 0x3377d1cf, v52
	v_fmac_f32_e32 v57, 0x3377d1cf, v53
	v_add_f32_e32 v54, v54, v56
	v_add_f32_e32 v55, v55, v57
	v_sub_f32_e32 v50, v50, v54
	v_sub_f32_e32 v51, v51, v55
	v_fmamk_f32 v80, v50, 0x3d800000, v79
	v_fmamk_f32 v81, v51, 0x3d800000, v80
	s_waitcnt lgkmcnt(0)
	ds_read_b128 v[34:37], v3 offset:1280
	ds_read_b128 v[38:41], v3 offset:1296
	ds_read_b128 v[42:45], v3 offset:1312
	ds_read_b128 v[46:49], v3 offset:1328
	ds_read_b128 v[200:203], v3 offset:1344
	ds_read_b128 v[204:207], v3 offset:1360
	ds_read_b128 v[208:211], v3 offset:1376
	ds_read_b128 v[212:215], v3 offset:1392
	global_load_ushort v172, v1, s[20:21]
	global_load_ushort v173, v1, s[20:21] offset:1024
	s_add_u32 s20, s20, 0x1a00
	s_addc_u32 s21, s21, 0
	global_load_ushort v174, v1, s[20:21]
	global_load_ushort v175, v1, s[20:21] offset:1024
	s_add_u32 s20, s20, 0x1a00
	s_addc_u32 s21, s21, 0
	v_fma_f32 v50, v16, v216, v32
	v_fma_f32 v51, v16, v236, v32
	v_fmac_f32_e32 v50, v17, v217
	v_fmac_f32_e32 v51, v17, v237
	v_fmac_f32_e32 v50, v18, v218
	v_fmac_f32_e32 v51, v18, v238
	v_fmac_f32_e32 v50, v19, v219
	v_fmac_f32_e32 v51, v19, v239
	v_fmac_f32_e32 v50, v20, v220
	v_fmac_f32_e32 v51, v20, v240
	v_fmac_f32_e32 v50, v21, v221
	v_fmac_f32_e32 v51, v21, v241
	v_fmac_f32_e32 v50, v22, v222
	v_fmac_f32_e32 v51, v22, v242
	v_fmac_f32_e32 v50, v23, v223
	v_fmac_f32_e32 v51, v23, v243
	v_fmac_f32_e32 v50, v24, v224
	v_fmac_f32_e32 v51, v24, v244
	v_fmac_f32_e32 v50, v25, v225
	v_fmac_f32_e32 v51, v25, v245
	v_fmac_f32_e32 v50, v26, v226
	v_fmac_f32_e32 v51, v26, v246
	v_fmac_f32_e32 v50, v27, v227
	v_fmac_f32_e32 v51, v27, v247
	v_fmac_f32_e32 v50, v28, v232
	v_fmac_f32_e32 v51, v28, v248
	v_fmac_f32_e32 v50, v29, v233
	v_fmac_f32_e32 v51, v29, v249
	v_fmac_f32_e32 v50, v30, v234
	v_fmac_f32_e32 v51, v30, v250
	v_fmac_f32_e32 v50, v31, v235
	v_fmac_f32_e32 v51, v31, v251
	v_mul_f32_e64 v52, |v50|, s7
	v_mul_f32_e64 v53, |v51|, s7
	v_exp_f32_e32 v52, v52
	v_exp_f32_e32 v53, v53
	v_min_f32_e32 v50, 0, v50
	v_add_f32_e32 v52, 1.0, v52
	v_add_f32_e32 v53, 1.0, v53
	v_log_f32_e32 v52, v52
	v_log_f32_e32 v53, v53
	v_min_f32_e32 v51, 0, v51
	v_mul_f32_e32 v54, 0x3f317217, v52
	v_mul_f32_e32 v55, 0x3f317217, v53
	v_fma_f32 v56, v52, s9, -v54
	v_fma_f32 v57, v53, s9, -v55
	v_fmac_f32_e32 v56, 0x3377d1cf, v52
	v_fmac_f32_e32 v57, 0x3377d1cf, v53
	v_add_f32_e32 v54, v54, v56
	v_add_f32_e32 v55, v55, v57
	v_sub_f32_e32 v50, v50, v54
	v_sub_f32_e32 v51, v51, v55
	v_fmamk_f32 v82, v50, 0x3d800000, v81
	v_fmamk_f32 v83, v51, 0x3d800000, v82
	s_waitcnt lgkmcnt(0)
	ds_read_b128 v[216:219], v3 offset:1408
	ds_read_b128 v[220:223], v3 offset:1424
	ds_read_b128 v[224:227], v3 offset:1440
	ds_read_b128 v[232:235], v3 offset:1456
	ds_read_b128 v[236:239], v3 offset:1472
	ds_read_b128 v[240:243], v3 offset:1488
	ds_read_b128 v[244:247], v3 offset:1504
	ds_read_b128 v[248:251], v3 offset:1520
	global_load_ushort v176, v1, s[20:21]
	global_load_ushort v177, v1, s[20:21] offset:1024
	s_add_u32 s20, s20, 0x1a00
	s_addc_u32 s21, s21, 0
	global_load_ushort v178, v1, s[20:21]
	global_load_ushort v179, v1, s[20:21] offset:1024
	s_add_u32 s20, s20, 0x1a00
	s_addc_u32 s21, s21, 0
	v_fma_f32 v50, v16, v34, v32
	v_fma_f32 v51, v16, v200, v32
	v_fmac_f32_e32 v50, v17, v35
	v_fmac_f32_e32 v51, v17, v201
	v_fmac_f32_e32 v50, v18, v36
	v_fmac_f32_e32 v51, v18, v202
	v_fmac_f32_e32 v50, v19, v37
	v_fmac_f32_e32 v51, v19, v203
	v_fmac_f32_e32 v50, v20, v38
	v_fmac_f32_e32 v51, v20, v204
	v_fmac_f32_e32 v50, v21, v39
	v_fmac_f32_e32 v51, v21, v205
	v_fmac_f32_e32 v50, v22, v40
	v_fmac_f32_e32 v51, v22, v206
	v_fmac_f32_e32 v50, v23, v41
	v_fmac_f32_e32 v51, v23, v207
	v_fmac_f32_e32 v50, v24, v42
	v_fmac_f32_e32 v51, v24, v208
	v_fmac_f32_e32 v50, v25, v43
	v_fmac_f32_e32 v51, v25, v209
	v_fmac_f32_e32 v50, v26, v44
	v_fmac_f32_e32 v51, v26, v210
	v_fmac_f32_e32 v50, v27, v45
	v_fmac_f32_e32 v51, v27, v211
	v_fmac_f32_e32 v50, v28, v46
	v_fmac_f32_e32 v51, v28, v212
	v_fmac_f32_e32 v50, v29, v47
	v_fmac_f32_e32 v51, v29, v213
	v_fmac_f32_e32 v50, v30, v48
	v_fmac_f32_e32 v51, v30, v214
	v_fmac_f32_e32 v50, v31, v49
	v_fmac_f32_e32 v51, v31, v215
	v_mul_f32_e64 v52, |v50|, s7
	v_mul_f32_e64 v53, |v51|, s7
	v_exp_f32_e32 v52, v52
	v_exp_f32_e32 v53, v53
	v_min_f32_e32 v50, 0, v50
	v_add_f32_e32 v52, 1.0, v52
	v_add_f32_e32 v53, 1.0, v53
	v_log_f32_e32 v52, v52
	v_log_f32_e32 v53, v53
	v_min_f32_e32 v51, 0, v51
	v_mul_f32_e32 v54, 0x3f317217, v52
	v_mul_f32_e32 v55, 0x3f317217, v53
	v_fma_f32 v56, v52, s9, -v54
	v_fma_f32 v57, v53, s9, -v55
	v_fmac_f32_e32 v56, 0x3377d1cf, v52
	v_fmac_f32_e32 v57, 0x3377d1cf, v53
	v_add_f32_e32 v54, v54, v56
	v_add_f32_e32 v55, v55, v57
	v_sub_f32_e32 v50, v50, v54
	v_sub_f32_e32 v51, v51, v55
	v_fmamk_f32 v84, v50, 0x3d800000, v83
	v_fmamk_f32 v85, v51, 0x3d800000, v84
	s_waitcnt lgkmcnt(0)
	ds_read_b128 v[34:37], v3 offset:1536
	ds_read_b128 v[38:41], v3 offset:1552
	ds_read_b128 v[42:45], v3 offset:1568
	ds_read_b128 v[46:49], v3 offset:1584
	ds_read_b128 v[200:203], v3 offset:1600
	ds_read_b128 v[204:207], v3 offset:1616
	ds_read_b128 v[208:211], v3 offset:1632
	ds_read_b128 v[212:215], v3 offset:1648
	global_load_ushort v180, v1, s[20:21]
	global_load_ushort v181, v1, s[20:21] offset:1024
	s_add_u32 s20, s20, 0x1a00
	s_addc_u32 s21, s21, 0
	global_load_ushort v182, v1, s[20:21]
	global_load_ushort v183, v1, s[20:21] offset:1024
	s_add_u32 s20, s20, 0x1a00
	s_addc_u32 s21, s21, 0
	v_fma_f32 v50, v16, v216, v32
	v_fma_f32 v51, v16, v236, v32
	v_fmac_f32_e32 v50, v17, v217
	v_fmac_f32_e32 v51, v17, v237
	v_fmac_f32_e32 v50, v18, v218
	v_fmac_f32_e32 v51, v18, v238
	v_fmac_f32_e32 v50, v19, v219
	v_fmac_f32_e32 v51, v19, v239
	v_fmac_f32_e32 v50, v20, v220
	v_fmac_f32_e32 v51, v20, v240
	v_fmac_f32_e32 v50, v21, v221
	v_fmac_f32_e32 v51, v21, v241
	v_fmac_f32_e32 v50, v22, v222
	v_fmac_f32_e32 v51, v22, v242
	v_fmac_f32_e32 v50, v23, v223
	v_fmac_f32_e32 v51, v23, v243
	v_fmac_f32_e32 v50, v24, v224
	v_fmac_f32_e32 v51, v24, v244
	v_fmac_f32_e32 v50, v25, v225
	v_fmac_f32_e32 v51, v25, v245
	v_fmac_f32_e32 v50, v26, v226
	v_fmac_f32_e32 v51, v26, v246
	v_fmac_f32_e32 v50, v27, v227
	v_fmac_f32_e32 v51, v27, v247
	v_fmac_f32_e32 v50, v28, v232
	v_fmac_f32_e32 v51, v28, v248
	v_fmac_f32_e32 v50, v29, v233
	v_fmac_f32_e32 v51, v29, v249
	v_fmac_f32_e32 v50, v30, v234
	v_fmac_f32_e32 v51, v30, v250
	v_fmac_f32_e32 v50, v31, v235
	v_fmac_f32_e32 v51, v31, v251
	v_mul_f32_e64 v52, |v50|, s7
	v_mul_f32_e64 v53, |v51|, s7
	v_exp_f32_e32 v52, v52
	v_exp_f32_e32 v53, v53
	v_min_f32_e32 v50, 0, v50
	v_add_f32_e32 v52, 1.0, v52
	v_add_f32_e32 v53, 1.0, v53
	v_log_f32_e32 v52, v52
	v_log_f32_e32 v53, v53
	v_min_f32_e32 v51, 0, v51
	v_mul_f32_e32 v54, 0x3f317217, v52
	v_mul_f32_e32 v55, 0x3f317217, v53
	v_fma_f32 v56, v52, s9, -v54
	v_fma_f32 v57, v53, s9, -v55
	v_fmac_f32_e32 v56, 0x3377d1cf, v52
	v_fmac_f32_e32 v57, 0x3377d1cf, v53
	v_add_f32_e32 v54, v54, v56
	v_add_f32_e32 v55, v55, v57
	v_sub_f32_e32 v50, v50, v54
	v_sub_f32_e32 v51, v51, v55
	v_fmamk_f32 v86, v50, 0x3d800000, v85
	v_fmamk_f32 v87, v51, 0x3d800000, v86
	s_waitcnt lgkmcnt(0)
	ds_read_b128 v[216:219], v3 offset:1664
	ds_read_b128 v[220:223], v3 offset:1680
	ds_read_b128 v[224:227], v3 offset:1696
	ds_read_b128 v[232:235], v3 offset:1712
	ds_read_b128 v[236:239], v3 offset:1728
	ds_read_b128 v[240:243], v3 offset:1744
	ds_read_b128 v[244:247], v3 offset:1760
	ds_read_b128 v[248:251], v3 offset:1776
	global_load_ushort v184, v1, s[20:21]
	global_load_ushort v185, v1, s[20:21] offset:1024
	s_add_u32 s20, s20, 0x1a00
	s_addc_u32 s21, s21, 0
	global_load_ushort v186, v1, s[20:21]
	global_load_ushort v187, v1, s[20:21] offset:1024
	s_add_u32 s20, s20, 0x1a00
	s_addc_u32 s21, s21, 0
	v_fma_f32 v50, v16, v34, v32
	v_fma_f32 v51, v16, v200, v32
	v_fmac_f32_e32 v50, v17, v35
	v_fmac_f32_e32 v51, v17, v201
	v_fmac_f32_e32 v50, v18, v36
	v_fmac_f32_e32 v51, v18, v202
	v_fmac_f32_e32 v50, v19, v37
	v_fmac_f32_e32 v51, v19, v203
	v_fmac_f32_e32 v50, v20, v38
	v_fmac_f32_e32 v51, v20, v204
	v_fmac_f32_e32 v50, v21, v39
	v_fmac_f32_e32 v51, v21, v205
	v_fmac_f32_e32 v50, v22, v40
	v_fmac_f32_e32 v51, v22, v206
	v_fmac_f32_e32 v50, v23, v41
	v_fmac_f32_e32 v51, v23, v207
	v_fmac_f32_e32 v50, v24, v42
	v_fmac_f32_e32 v51, v24, v208
	v_fmac_f32_e32 v50, v25, v43
	v_fmac_f32_e32 v51, v25, v209
	v_fmac_f32_e32 v50, v26, v44
	v_fmac_f32_e32 v51, v26, v210
	v_fmac_f32_e32 v50, v27, v45
	v_fmac_f32_e32 v51, v27, v211
	v_fmac_f32_e32 v50, v28, v46
	v_fmac_f32_e32 v51, v28, v212
	v_fmac_f32_e32 v50, v29, v47
	v_fmac_f32_e32 v51, v29, v213
	v_fmac_f32_e32 v50, v30, v48
	v_fmac_f32_e32 v51, v30, v214
	v_fmac_f32_e32 v50, v31, v49
	v_fmac_f32_e32 v51, v31, v215
	v_mul_f32_e64 v52, |v50|, s7
	v_mul_f32_e64 v53, |v51|, s7
	v_exp_f32_e32 v52, v52
	v_exp_f32_e32 v53, v53
	v_min_f32_e32 v50, 0, v50
	v_add_f32_e32 v52, 1.0, v52
	v_add_f32_e32 v53, 1.0, v53
	v_log_f32_e32 v52, v52
	v_log_f32_e32 v53, v53
	v_min_f32_e32 v51, 0, v51
	v_mul_f32_e32 v54, 0x3f317217, v52
	v_mul_f32_e32 v55, 0x3f317217, v53
	v_fma_f32 v56, v52, s9, -v54
	v_fma_f32 v57, v53, s9, -v55
	v_fmac_f32_e32 v56, 0x3377d1cf, v52
	v_fmac_f32_e32 v57, 0x3377d1cf, v53
	v_add_f32_e32 v54, v54, v56
	v_add_f32_e32 v55, v55, v57
	v_sub_f32_e32 v50, v50, v54
	v_sub_f32_e32 v51, v51, v55
	v_fmamk_f32 v88, v50, 0x3d800000, v87
	v_fmamk_f32 v89, v51, 0x3d800000, v88
	s_waitcnt lgkmcnt(0)
	ds_read_b128 v[34:37], v3 offset:1792
	ds_read_b128 v[38:41], v3 offset:1808
	ds_read_b128 v[42:45], v3 offset:1824
	ds_read_b128 v[46:49], v3 offset:1840
	ds_read_b128 v[200:203], v3 offset:1856
	ds_read_b128 v[204:207], v3 offset:1872
	ds_read_b128 v[208:211], v3 offset:1888
	ds_read_b128 v[212:215], v3 offset:1904
	global_load_ushort v188, v1, s[20:21]
	global_load_ushort v189, v1, s[20:21] offset:1024
	s_add_u32 s20, s20, 0x1a00
	s_addc_u32 s21, s21, 0
	global_load_ushort v190, v1, s[20:21]
	global_load_ushort v191, v1, s[20:21] offset:1024
	s_add_u32 s20, s20, 0x1a00
	s_addc_u32 s21, s21, 0
	v_fma_f32 v50, v16, v216, v32
	v_fma_f32 v51, v16, v236, v32
	v_fmac_f32_e32 v50, v17, v217
	v_fmac_f32_e32 v51, v17, v237
	v_fmac_f32_e32 v50, v18, v218
	v_fmac_f32_e32 v51, v18, v238
	v_fmac_f32_e32 v50, v19, v219
	v_fmac_f32_e32 v51, v19, v239
	v_fmac_f32_e32 v50, v20, v220
	v_fmac_f32_e32 v51, v20, v240
	v_fmac_f32_e32 v50, v21, v221
	v_fmac_f32_e32 v51, v21, v241
	v_fmac_f32_e32 v50, v22, v222
	v_fmac_f32_e32 v51, v22, v242
	v_fmac_f32_e32 v50, v23, v223
	v_fmac_f32_e32 v51, v23, v243
	v_fmac_f32_e32 v50, v24, v224
	v_fmac_f32_e32 v51, v24, v244
	v_fmac_f32_e32 v50, v25, v225
	v_fmac_f32_e32 v51, v25, v245
	v_fmac_f32_e32 v50, v26, v226
	v_fmac_f32_e32 v51, v26, v246
	v_fmac_f32_e32 v50, v27, v227
	v_fmac_f32_e32 v51, v27, v247
	v_fmac_f32_e32 v50, v28, v232
	v_fmac_f32_e32 v51, v28, v248
	v_fmac_f32_e32 v50, v29, v233
	v_fmac_f32_e32 v51, v29, v249
	v_fmac_f32_e32 v50, v30, v234
	v_fmac_f32_e32 v51, v30, v250
	v_fmac_f32_e32 v50, v31, v235
	v_fmac_f32_e32 v51, v31, v251
	v_mul_f32_e64 v52, |v50|, s7
	v_mul_f32_e64 v53, |v51|, s7
	v_exp_f32_e32 v52, v52
	v_exp_f32_e32 v53, v53
	v_min_f32_e32 v50, 0, v50
	v_add_f32_e32 v52, 1.0, v52
	v_add_f32_e32 v53, 1.0, v53
	v_log_f32_e32 v52, v52
	v_log_f32_e32 v53, v53
	v_min_f32_e32 v51, 0, v51
	v_mul_f32_e32 v54, 0x3f317217, v52
	v_mul_f32_e32 v55, 0x3f317217, v53
	v_fma_f32 v56, v52, s9, -v54
	v_fma_f32 v57, v53, s9, -v55
	v_fmac_f32_e32 v56, 0x3377d1cf, v52
	v_fmac_f32_e32 v57, 0x3377d1cf, v53
	v_add_f32_e32 v54, v54, v56
	v_add_f32_e32 v55, v55, v57
	v_sub_f32_e32 v50, v50, v54
	v_sub_f32_e32 v51, v51, v55
	v_fmamk_f32 v90, v50, 0x3d800000, v89
	v_fmamk_f32 v91, v51, 0x3d800000, v90
	s_waitcnt lgkmcnt(0)
	ds_read_b128 v[216:219], v3 offset:1920
	ds_read_b128 v[220:223], v3 offset:1936
	ds_read_b128 v[224:227], v3 offset:1952
	ds_read_b128 v[232:235], v3 offset:1968
	ds_read_b128 v[236:239], v3 offset:1984
	ds_read_b128 v[240:243], v3 offset:2000
	ds_read_b128 v[244:247], v3 offset:2016
	ds_read_b128 v[248:251], v3 offset:2032
	s_waitcnt vmcnt(56)
	global_load_ushort v192, v1, s[20:21]
	global_load_ushort v193, v1, s[20:21] offset:1024
	s_add_u32 s20, s20, 0x1a00
	s_addc_u32 s21, s21, 0
	global_load_ushort v194, v1, s[20:21]
	global_load_ushort v195, v1, s[20:21] offset:1024
	s_add_u32 s20, s20, 0x1a00
	s_addc_u32 s21, s21, 0
	v_fma_f32 v50, v16, v34, v32
	v_fma_f32 v51, v16, v200, v32
	v_fmac_f32_e32 v50, v17, v35
	v_fmac_f32_e32 v51, v17, v201
	v_fmac_f32_e32 v50, v18, v36
	v_fmac_f32_e32 v51, v18, v202
	v_fmac_f32_e32 v50, v19, v37
	v_fmac_f32_e32 v51, v19, v203
	v_fmac_f32_e32 v50, v20, v38
	v_fmac_f32_e32 v51, v20, v204
	v_fmac_f32_e32 v50, v21, v39
	v_fmac_f32_e32 v51, v21, v205
	v_fmac_f32_e32 v50, v22, v40
	v_fmac_f32_e32 v51, v22, v206
	v_fmac_f32_e32 v50, v23, v41
	v_fmac_f32_e32 v51, v23, v207
	v_fmac_f32_e32 v50, v24, v42
	v_fmac_f32_e32 v51, v24, v208
	v_fmac_f32_e32 v50, v25, v43
	v_fmac_f32_e32 v51, v25, v209
	v_fmac_f32_e32 v50, v26, v44
	v_fmac_f32_e32 v51, v26, v210
	v_fmac_f32_e32 v50, v27, v45
	v_fmac_f32_e32 v51, v27, v211
	v_fmac_f32_e32 v50, v28, v46
	v_fmac_f32_e32 v51, v28, v212
	v_fmac_f32_e32 v50, v29, v47
	v_fmac_f32_e32 v51, v29, v213
	v_fmac_f32_e32 v50, v30, v48
	v_fmac_f32_e32 v51, v30, v214
	v_fmac_f32_e32 v50, v31, v49
	v_fmac_f32_e32 v51, v31, v215
	v_mul_f32_e64 v52, |v50|, s7
	v_mul_f32_e64 v53, |v51|, s7
	v_exp_f32_e32 v52, v52
	v_exp_f32_e32 v53, v53
	v_min_f32_e32 v50, 0, v50
	v_add_f32_e32 v52, 1.0, v52
	v_add_f32_e32 v53, 1.0, v53
	v_log_f32_e32 v52, v52
	v_log_f32_e32 v53, v53
	v_min_f32_e32 v51, 0, v51
	v_mul_f32_e32 v54, 0x3f317217, v52
	v_mul_f32_e32 v55, 0x3f317217, v53
	v_fma_f32 v56, v52, s9, -v54
	v_fma_f32 v57, v53, s9, -v55
	v_fmac_f32_e32 v56, 0x3377d1cf, v52
	v_fmac_f32_e32 v57, 0x3377d1cf, v53
	v_add_f32_e32 v54, v54, v56
	v_add_f32_e32 v55, v55, v57
	v_sub_f32_e32 v50, v50, v54
	v_sub_f32_e32 v51, v51, v55
	v_fmamk_f32 v92, v50, 0x3d800000, v91
	v_fmamk_f32 v93, v51, 0x3d800000, v92
	s_waitcnt lgkmcnt(0)
	ds_read_b128 v[34:37], v3 offset:2048
	ds_read_b128 v[38:41], v3 offset:2064
	ds_read_b128 v[42:45], v3 offset:2080
	ds_read_b128 v[46:49], v3 offset:2096
	ds_read_b128 v[200:203], v3 offset:2112
	ds_read_b128 v[204:207], v3 offset:2128
	ds_read_b128 v[208:211], v3 offset:2144
	ds_read_b128 v[212:215], v3 offset:2160
	s_waitcnt vmcnt(56)
	global_load_ushort v196, v1, s[20:21]
	global_load_ushort v197, v1, s[20:21] offset:1024
	s_add_u32 s20, s20, 0x1a00
	s_addc_u32 s21, s21, 0
	global_load_ushort v198, v1, s[20:21]
	global_load_ushort v199, v1, s[20:21] offset:1024
	s_add_u32 s20, s20, 0x1a00
	s_addc_u32 s21, s21, 0
	v_fma_f32 v50, v16, v216, v32
	v_fma_f32 v51, v16, v236, v32
	v_fmac_f32_e32 v50, v17, v217
	v_fmac_f32_e32 v51, v17, v237
	v_fmac_f32_e32 v50, v18, v218
	v_fmac_f32_e32 v51, v18, v238
	v_fmac_f32_e32 v50, v19, v219
	v_fmac_f32_e32 v51, v19, v239
	v_fmac_f32_e32 v50, v20, v220
	v_fmac_f32_e32 v51, v20, v240
	v_fmac_f32_e32 v50, v21, v221
	v_fmac_f32_e32 v51, v21, v241
	v_fmac_f32_e32 v50, v22, v222
	v_fmac_f32_e32 v51, v22, v242
	v_fmac_f32_e32 v50, v23, v223
	v_fmac_f32_e32 v51, v23, v243
	v_fmac_f32_e32 v50, v24, v224
	v_fmac_f32_e32 v51, v24, v244
	v_fmac_f32_e32 v50, v25, v225
	v_fmac_f32_e32 v51, v25, v245
	v_fmac_f32_e32 v50, v26, v226
	v_fmac_f32_e32 v51, v26, v246
	v_fmac_f32_e32 v50, v27, v227
	v_fmac_f32_e32 v51, v27, v247
	v_fmac_f32_e32 v50, v28, v232
	v_fmac_f32_e32 v51, v28, v248
	v_fmac_f32_e32 v50, v29, v233
	v_fmac_f32_e32 v51, v29, v249
	v_fmac_f32_e32 v50, v30, v234
	v_fmac_f32_e32 v51, v30, v250
	v_fmac_f32_e32 v50, v31, v235
	v_fmac_f32_e32 v51, v31, v251
	v_mul_f32_e64 v52, |v50|, s7
	v_mul_f32_e64 v53, |v51|, s7
	v_exp_f32_e32 v52, v52
	v_exp_f32_e32 v53, v53
	v_min_f32_e32 v50, 0, v50
	v_add_f32_e32 v52, 1.0, v52
	v_add_f32_e32 v53, 1.0, v53
	v_log_f32_e32 v52, v52
	v_log_f32_e32 v53, v53
	v_min_f32_e32 v51, 0, v51
	v_mul_f32_e32 v54, 0x3f317217, v52
	v_mul_f32_e32 v55, 0x3f317217, v53
	v_fma_f32 v56, v52, s9, -v54
	v_fma_f32 v57, v53, s9, -v55
	v_fmac_f32_e32 v56, 0x3377d1cf, v52
	v_fmac_f32_e32 v57, 0x3377d1cf, v53
	v_add_f32_e32 v54, v54, v56
	v_add_f32_e32 v55, v55, v57
	v_sub_f32_e32 v50, v50, v54
	v_sub_f32_e32 v51, v51, v55
	v_fmamk_f32 v94, v50, 0x3d800000, v93
	v_fmamk_f32 v95, v51, 0x3d800000, v94
	s_waitcnt lgkmcnt(0)
	ds_read_b128 v[216:219], v3 offset:2176
	ds_read_b128 v[220:223], v3 offset:2192
	ds_read_b128 v[224:227], v3 offset:2208
	ds_read_b128 v[232:235], v3 offset:2224
	ds_read_b128 v[236:239], v3 offset:2240
	ds_read_b128 v[240:243], v3 offset:2256
	ds_read_b128 v[244:247], v3 offset:2272
	ds_read_b128 v[248:251], v3 offset:2288
	v_fma_f32 v50, v16, v34, v32
	v_fma_f32 v51, v16, v200, v32
	v_fmac_f32_e32 v50, v17, v35
	v_fmac_f32_e32 v51, v17, v201
	v_fmac_f32_e32 v50, v18, v36
	v_fmac_f32_e32 v51, v18, v202
	v_fmac_f32_e32 v50, v19, v37
	v_fmac_f32_e32 v51, v19, v203
	v_fmac_f32_e32 v50, v20, v38
	v_fmac_f32_e32 v51, v20, v204
	v_fmac_f32_e32 v50, v21, v39
	v_fmac_f32_e32 v51, v21, v205
	v_fmac_f32_e32 v50, v22, v40
	v_fmac_f32_e32 v51, v22, v206
	v_fmac_f32_e32 v50, v23, v41
	v_fmac_f32_e32 v51, v23, v207
	v_fmac_f32_e32 v50, v24, v42
	v_fmac_f32_e32 v51, v24, v208
	v_fmac_f32_e32 v50, v25, v43
	v_fmac_f32_e32 v51, v25, v209
	v_fmac_f32_e32 v50, v26, v44
	v_fmac_f32_e32 v51, v26, v210
	v_fmac_f32_e32 v50, v27, v45
	v_fmac_f32_e32 v51, v27, v211
	v_fmac_f32_e32 v50, v28, v46
	v_fmac_f32_e32 v51, v28, v212
	v_fmac_f32_e32 v50, v29, v47
	v_fmac_f32_e32 v51, v29, v213
	v_fmac_f32_e32 v50, v30, v48
	v_fmac_f32_e32 v51, v30, v214
	v_fmac_f32_e32 v50, v31, v49
	v_fmac_f32_e32 v51, v31, v215
	v_mul_f32_e64 v52, |v50|, s7
	v_mul_f32_e64 v53, |v51|, s7
	v_exp_f32_e32 v52, v52
	v_exp_f32_e32 v53, v53
	v_min_f32_e32 v50, 0, v50
	v_add_f32_e32 v52, 1.0, v52
	v_add_f32_e32 v53, 1.0, v53
	v_log_f32_e32 v52, v52
	v_log_f32_e32 v53, v53
	v_min_f32_e32 v51, 0, v51
	v_mul_f32_e32 v54, 0x3f317217, v52
	v_mul_f32_e32 v55, 0x3f317217, v53
	v_fma_f32 v56, v52, s9, -v54
	v_fma_f32 v57, v53, s9, -v55
	v_fmac_f32_e32 v56, 0x3377d1cf, v52
	v_fmac_f32_e32 v57, 0x3377d1cf, v53
	v_add_f32_e32 v54, v54, v56
	v_add_f32_e32 v55, v55, v57
	v_sub_f32_e32 v50, v50, v54
	v_sub_f32_e32 v51, v51, v55
	v_fmamk_f32 v96, v50, 0x3d800000, v95
	v_fmamk_f32 v97, v51, 0x3d800000, v96
	s_waitcnt vmcnt(0)
	v_sub_f32_e32 v52, v64, v96
	v_lshlrev_b32_e32 v50, 16, v136
	v_mul_f32_e32 v52, 0x3fb8aa3b, v52
	v_lshlrev_b32_e32 v51, 16, v137
	v_exp_f32_e32 v53, v52
	v_exp_f32_e64 v54, -v52
	v_mul_f32_e32 v50, 0x3db504f3, v50
	s_nop 0
	v_mul_f32_e32 v50, v53, v50
	v_mul_f32_e32 v8, v54, v51
	v_cvt_pk_bf16_f32 v50, v50, v8
	global_store_short v1, v50, s[22:23]
	global_store_short_d16_hi v1, v50, s[22:23] offset:1024
	s_add_u32 s22, s22, 0x1a00
	s_addc_u32 s23, s23, 0
	global_load_ushort v136, v1, s[20:21]
	global_load_ushort v137, v1, s[20:21] offset:1024
	s_add_u32 s20, s20, 0x1a00
	s_addc_u32 s21, s21, 0
	v_sub_f32_e32 v52, v65, v96
	v_lshlrev_b32_e32 v50, 16, v138
	v_mul_f32_e32 v52, 0x3fb8aa3b, v52
	v_lshlrev_b32_e32 v51, 16, v139
	v_exp_f32_e32 v53, v52
	v_exp_f32_e64 v54, -v52
	v_mul_f32_e32 v50, 0x3db504f3, v50
	s_nop 0
	v_mul_f32_e32 v50, v53, v50
	v_mul_f32_e32 v9, v54, v51
	v_cvt_pk_bf16_f32 v50, v50, v9
	global_store_short v1, v50, s[22:23]
	global_store_short_d16_hi v1, v50, s[22:23] offset:1024
	s_add_u32 s22, s22, 0x1a00
	s_addc_u32 s23, s23, 0
	global_load_ushort v138, v1, s[20:21]
	global_load_ushort v139, v1, s[20:21] offset:1024
	s_add_u32 s20, s20, 0x1a00
	s_addc_u32 s21, s21, 0
	v_sub_f32_e32 v52, v66, v96
	v_lshlrev_b32_e32 v50, 16, v140
	v_mul_f32_e32 v52, 0x3fb8aa3b, v52
	v_lshlrev_b32_e32 v51, 16, v141
	v_exp_f32_e32 v53, v52
	v_exp_f32_e64 v54, -v52
	v_mul_f32_e32 v50, 0x3db504f3, v50
	s_nop 0
	v_mul_f32_e32 v50, v53, v50
	v_mul_f32_e32 v10, v54, v51
	v_cvt_pk_bf16_f32 v50, v50, v10
	global_store_short v1, v50, s[22:23]
	global_store_short_d16_hi v1, v50, s[22:23] offset:1024
	s_add_u32 s22, s22, 0x1a00
	s_addc_u32 s23, s23, 0
	global_load_ushort v140, v1, s[20:21]
	global_load_ushort v141, v1, s[20:21] offset:1024
	s_add_u32 s20, s20, 0x1a00
	s_addc_u32 s21, s21, 0
	v_sub_f32_e32 v52, v67, v96
	v_lshlrev_b32_e32 v50, 16, v142
	v_mul_f32_e32 v52, 0x3fb8aa3b, v52
	v_lshlrev_b32_e32 v51, 16, v143
	v_exp_f32_e32 v53, v52
	v_exp_f32_e64 v54, -v52
	v_mul_f32_e32 v50, 0x3db504f3, v50
	s_nop 0
	v_mul_f32_e32 v50, v53, v50
	v_mul_f32_e32 v11, v54, v51
	v_cvt_pk_bf16_f32 v50, v50, v11
	global_store_short v1, v50, s[22:23]
	global_store_short_d16_hi v1, v50, s[22:23] offset:1024
	s_add_u32 s22, s22, 0x1a00
	s_addc_u32 s23, s23, 0
	global_load_ushort v142, v1, s[20:21]
	global_load_ushort v143, v1, s[20:21] offset:1024
	s_add_u32 s20, s20, 0x1a00
	s_addc_u32 s21, s21, 0
	v_sub_f32_e32 v52, v68, v96
	v_lshlrev_b32_e32 v50, 16, v144
	v_mul_f32_e32 v52, 0x3fb8aa3b, v52
	v_lshlrev_b32_e32 v51, 16, v145
	v_exp_f32_e32 v53, v52
	v_exp_f32_e64 v54, -v52
	v_mul_f32_e32 v50, 0x3db504f3, v50
	s_nop 0
	v_mul_f32_e32 v50, v53, v50
	v_mul_f32_e32 v12, v54, v51
	v_cvt_pk_bf16_f32 v50, v50, v12
	global_store_short v1, v50, s[22:23]
	global_store_short_d16_hi v1, v50, s[22:23] offset:1024
	s_add_u32 s22, s22, 0x1a00
	s_addc_u32 s23, s23, 0
	global_load_ushort v144, v1, s[20:21]
	global_load_ushort v145, v1, s[20:21] offset:1024
	s_add_u32 s20, s20, 0x1a00
	s_addc_u32 s21, s21, 0
	v_sub_f32_e32 v52, v69, v96
	v_lshlrev_b32_e32 v50, 16, v146
	v_mul_f32_e32 v52, 0x3fb8aa3b, v52
	v_lshlrev_b32_e32 v51, 16, v147
	v_exp_f32_e32 v53, v52
	v_exp_f32_e64 v54, -v52
	v_mul_f32_e32 v50, 0x3db504f3, v50
	s_nop 0
	v_mul_f32_e32 v50, v53, v50
	v_mul_f32_e32 v13, v54, v51
	v_cvt_pk_bf16_f32 v50, v50, v13
	global_store_short v1, v50, s[22:23]
	global_store_short_d16_hi v1, v50, s[22:23] offset:1024
	s_add_u32 s22, s22, 0x1a00
	s_addc_u32 s23, s23, 0
	global_load_ushort v146, v1, s[20:21]
	global_load_ushort v147, v1, s[20:21] offset:1024
	s_add_u32 s20, s20, 0x1a00
	s_addc_u32 s21, s21, 0
	v_sub_f32_e32 v52, v70, v96
	v_lshlrev_b32_e32 v50, 16, v148
	v_mul_f32_e32 v52, 0x3fb8aa3b, v52
	v_lshlrev_b32_e32 v51, 16, v149
	v_exp_f32_e32 v53, v52
	v_exp_f32_e64 v54, -v52
	v_mul_f32_e32 v50, 0x3db504f3, v50
	s_nop 0
	v_mul_f32_e32 v50, v53, v50
	v_mul_f32_e32 v14, v54, v51
	v_cvt_pk_bf16_f32 v50, v50, v14
	global_store_short v1, v50, s[22:23]
	global_store_short_d16_hi v1, v50, s[22:23] offset:1024
	s_add_u32 s22, s22, 0x1a00
	s_addc_u32 s23, s23, 0
	global_load_ushort v148, v1, s[20:21]
	global_load_ushort v149, v1, s[20:21] offset:1024
	s_add_u32 s20, s20, 0x1a00
	s_addc_u32 s21, s21, 0
	v_sub_f32_e32 v52, v71, v96
	v_lshlrev_b32_e32 v50, 16, v150
	v_mul_f32_e32 v52, 0x3fb8aa3b, v52
	v_lshlrev_b32_e32 v51, 16, v151
	v_exp_f32_e32 v53, v52
	v_exp_f32_e64 v54, -v52
	v_mul_f32_e32 v50, 0x3db504f3, v50
	s_nop 0
	v_mul_f32_e32 v50, v53, v50
	v_mul_f32_e32 v15, v54, v51
	v_cvt_pk_bf16_f32 v50, v50, v15
	global_store_short v1, v50, s[22:23]
	global_store_short_d16_hi v1, v50, s[22:23] offset:1024
	s_add_u32 s22, s22, 0x1a00
	s_addc_u32 s23, s23, 0
	v_cvt_pk_bf16_f32 v4, v8, v9
	v_cvt_pk_bf16_f32 v5, v10, v11
	v_cvt_pk_bf16_f32 v6, v12, v13
	v_cvt_pk_bf16_f32 v7, v14, v15
	global_store_dwordx4 v2, v[4:7], s[26:27] offset:0
	global_load_ushort v150, v1, s[20:21]
	global_load_ushort v151, v1, s[20:21] offset:1024
	s_add_u32 s20, s20, 0x1a00
	s_addc_u32 s21, s21, 0
	v_sub_f32_e32 v52, v72, v96
	v_lshlrev_b32_e32 v50, 16, v152
	v_mul_f32_e32 v52, 0x3fb8aa3b, v52
	v_lshlrev_b32_e32 v51, 16, v153
	v_exp_f32_e32 v53, v52
	v_exp_f32_e64 v54, -v52
	v_mul_f32_e32 v50, 0x3db504f3, v50
	s_nop 0
	v_mul_f32_e32 v50, v53, v50
	v_mul_f32_e32 v8, v54, v51
	v_cvt_pk_bf16_f32 v50, v50, v8
	global_store_short v1, v50, s[22:23]
	global_store_short_d16_hi v1, v50, s[22:23] offset:1024
	s_add_u32 s22, s22, 0x1a00
	s_addc_u32 s23, s23, 0
	global_load_ushort v152, v1, s[20:21]
	global_load_ushort v153, v1, s[20:21] offset:1024
	s_add_u32 s20, s20, 0x1a00
	s_addc_u32 s21, s21, 0
	v_sub_f32_e32 v52, v73, v96
	v_lshlrev_b32_e32 v50, 16, v154
	v_mul_f32_e32 v52, 0x3fb8aa3b, v52
	v_lshlrev_b32_e32 v51, 16, v155
	v_exp_f32_e32 v53, v52
	v_exp_f32_e64 v54, -v52
	v_mul_f32_e32 v50, 0x3db504f3, v50
	s_nop 0
	v_mul_f32_e32 v50, v53, v50
	v_mul_f32_e32 v9, v54, v51
	v_cvt_pk_bf16_f32 v50, v50, v9
	global_store_short v1, v50, s[22:23]
	global_store_short_d16_hi v1, v50, s[22:23] offset:1024
	s_add_u32 s22, s22, 0x1a00
	s_addc_u32 s23, s23, 0
	global_load_ushort v154, v1, s[20:21]
	global_load_ushort v155, v1, s[20:21] offset:1024
	s_add_u32 s20, s20, 0x1a00
	s_addc_u32 s21, s21, 0
	v_sub_f32_e32 v52, v74, v96
	v_lshlrev_b32_e32 v50, 16, v156
	v_mul_f32_e32 v52, 0x3fb8aa3b, v52
	v_lshlrev_b32_e32 v51, 16, v157
	v_exp_f32_e32 v53, v52
	v_exp_f32_e64 v54, -v52
	v_mul_f32_e32 v50, 0x3db504f3, v50
	s_nop 0
	v_mul_f32_e32 v50, v53, v50
	v_mul_f32_e32 v10, v54, v51
	v_cvt_pk_bf16_f32 v50, v50, v10
	global_store_short v1, v50, s[22:23]
	global_store_short_d16_hi v1, v50, s[22:23] offset:1024
	s_add_u32 s22, s22, 0x1a00
	s_addc_u32 s23, s23, 0
	global_load_ushort v156, v1, s[20:21]
	global_load_ushort v157, v1, s[20:21] offset:1024
	s_add_u32 s20, s20, 0x1a00
	s_addc_u32 s21, s21, 0
	v_sub_f32_e32 v52, v75, v96
	v_lshlrev_b32_e32 v50, 16, v158
	v_mul_f32_e32 v52, 0x3fb8aa3b, v52
	v_lshlrev_b32_e32 v51, 16, v159
	v_exp_f32_e32 v53, v52
	v_exp_f32_e64 v54, -v52
	v_mul_f32_e32 v50, 0x3db504f3, v50
	s_nop 0
	v_mul_f32_e32 v50, v53, v50
	v_mul_f32_e32 v11, v54, v51
	v_cvt_pk_bf16_f32 v50, v50, v11
	global_store_short v1, v50, s[22:23]
	global_store_short_d16_hi v1, v50, s[22:23] offset:1024
	s_add_u32 s22, s22, 0x1a00
	s_addc_u32 s23, s23, 0
	global_load_ushort v158, v1, s[20:21]
	global_load_ushort v159, v1, s[20:21] offset:1024
	s_add_u32 s20, s20, 0x1a00
	s_addc_u32 s21, s21, 0
	s_waitcnt vmcnt(52)
	v_sub_f32_e32 v52, v76, v96
	v_lshlrev_b32_e32 v50, 16, v160
	v_mul_f32_e32 v52, 0x3fb8aa3b, v52
	v_lshlrev_b32_e32 v51, 16, v161
	v_exp_f32_e32 v53, v52
	v_exp_f32_e64 v54, -v52
	v_mul_f32_e32 v50, 0x3db504f3, v50
	s_nop 0
	v_mul_f32_e32 v50, v53, v50
	v_mul_f32_e32 v12, v54, v51
	v_cvt_pk_bf16_f32 v50, v50, v12
	global_store_short v1, v50, s[22:23]
	global_store_short_d16_hi v1, v50, s[22:23] offset:1024
	s_add_u32 s22, s22, 0x1a00
	s_addc_u32 s23, s23, 0
	global_load_ushort v160, v1, s[20:21]
	global_load_ushort v161, v1, s[20:21] offset:1024
	s_add_u32 s20, s20, 0x1a00
	s_addc_u32 s21, s21, 0
	s_waitcnt vmcnt(52)
	v_sub_f32_e32 v52, v77, v96
	v_lshlrev_b32_e32 v50, 16, v162
	v_mul_f32_e32 v52, 0x3fb8aa3b, v52
	v_lshlrev_b32_e32 v51, 16, v163
	v_exp_f32_e32 v53, v52
	v_exp_f32_e64 v54, -v52
	v_mul_f32_e32 v50, 0x3db504f3, v50
	s_nop 0
	v_mul_f32_e32 v50, v53, v50
	v_mul_f32_e32 v13, v54, v51
	v_cvt_pk_bf16_f32 v50, v50, v13
	global_store_short v1, v50, s[22:23]
	global_store_short_d16_hi v1, v50, s[22:23] offset:1024
	s_add_u32 s22, s22, 0x1a00
	s_addc_u32 s23, s23, 0
	global_load_ushort v162, v1, s[20:21]
	global_load_ushort v163, v1, s[20:21] offset:1024
	s_add_u32 s20, s20, 0x1a00
	s_addc_u32 s21, s21, 0
	s_waitcnt vmcnt(52)
	v_sub_f32_e32 v52, v78, v96
	v_lshlrev_b32_e32 v50, 16, v164
	v_mul_f32_e32 v52, 0x3fb8aa3b, v52
	v_lshlrev_b32_e32 v51, 16, v165
	v_exp_f32_e32 v53, v52
	v_exp_f32_e64 v54, -v52
	v_mul_f32_e32 v50, 0x3db504f3, v50
	s_nop 0
	v_mul_f32_e32 v50, v53, v50
	v_mul_f32_e32 v14, v54, v51
	v_cvt_pk_bf16_f32 v50, v50, v14
	global_store_short v1, v50, s[22:23]
	global_store_short_d16_hi v1, v50, s[22:23] offset:1024
	s_add_u32 s22, s22, 0x1a00
	s_addc_u32 s23, s23, 0
	global_load_ushort v164, v1, s[20:21]
	global_load_ushort v165, v1, s[20:21] offset:1024
	s_add_u32 s20, s20, 0x1a00
	s_addc_u32 s21, s21, 0
	s_waitcnt vmcnt(52)
	v_sub_f32_e32 v52, v79, v96
	v_lshlrev_b32_e32 v50, 16, v166
	v_mul_f32_e32 v52, 0x3fb8aa3b, v52
	v_lshlrev_b32_e32 v51, 16, v167
	v_exp_f32_e32 v53, v52
	v_exp_f32_e64 v54, -v52
	v_mul_f32_e32 v50, 0x3db504f3, v50
	s_nop 0
	v_mul_f32_e32 v50, v53, v50
	v_mul_f32_e32 v15, v54, v51
	v_cvt_pk_bf16_f32 v50, v50, v15
	global_store_short v1, v50, s[22:23]
	global_store_short_d16_hi v1, v50, s[22:23] offset:1024
	s_add_u32 s22, s22, 0x1a00
	s_addc_u32 s23, s23, 0
	v_cvt_pk_bf16_f32 v4, v8, v9
	v_cvt_pk_bf16_f32 v5, v10, v11
	v_cvt_pk_bf16_f32 v6, v12, v13
	v_cvt_pk_bf16_f32 v7, v14, v15
	global_store_dwordx4 v2, v[4:7], s[26:27] offset:16
	global_load_ushort v166, v1, s[20:21]
	global_load_ushort v167, v1, s[20:21] offset:1024
	s_add_u32 s20, s20, 0x1a00
	s_addc_u32 s21, s21, 0
	s_waitcnt vmcnt(52)
	v_sub_f32_e32 v52, v80, v96
	v_lshlrev_b32_e32 v50, 16, v168
	v_mul_f32_e32 v52, 0x3fb8aa3b, v52
	v_lshlrev_b32_e32 v51, 16, v169
	v_exp_f32_e32 v53, v52
	v_exp_f32_e64 v54, -v52
	v_mul_f32_e32 v50, 0x3db504f3, v50
	s_nop 0
	v_mul_f32_e32 v50, v53, v50
	v_mul_f32_e32 v8, v54, v51
	v_cvt_pk_bf16_f32 v50, v50, v8
	global_store_short v1, v50, s[22:23]
	global_store_short_d16_hi v1, v50, s[22:23] offset:1024
	s_add_u32 s22, s22, 0x1a00
	s_addc_u32 s23, s23, 0
	global_load_ushort v168, v1, s[20:21]
	global_load_ushort v169, v1, s[20:21] offset:1024
	s_add_u32 s20, s20, 0x1a00
	s_addc_u32 s21, s21, 0
	s_waitcnt vmcnt(52)
	v_sub_f32_e32 v52, v81, v96
	v_lshlrev_b32_e32 v50, 16, v170
	v_mul_f32_e32 v52, 0x3fb8aa3b, v52
	v_lshlrev_b32_e32 v51, 16, v171
	v_exp_f32_e32 v53, v52
	v_exp_f32_e64 v54, -v52
	v_mul_f32_e32 v50, 0x3db504f3, v50
	s_nop 0
	v_mul_f32_e32 v50, v53, v50
	v_mul_f32_e32 v9, v54, v51
	v_cvt_pk_bf16_f32 v50, v50, v9
	global_store_short v1, v50, s[22:23]
	global_store_short_d16_hi v1, v50, s[22:23] offset:1024
	s_add_u32 s22, s22, 0x1a00
	s_addc_u32 s23, s23, 0
	global_load_ushort v170, v1, s[20:21]
	global_load_ushort v171, v1, s[20:21] offset:1024
	s_add_u32 s20, s20, 0x1a00
	s_addc_u32 s21, s21, 0
	s_waitcnt vmcnt(52)
	v_sub_f32_e32 v52, v82, v96
	v_lshlrev_b32_e32 v50, 16, v172
	v_mul_f32_e32 v52, 0x3fb8aa3b, v52
	v_lshlrev_b32_e32 v51, 16, v173
	v_exp_f32_e32 v53, v52
	v_exp_f32_e64 v54, -v52
	v_mul_f32_e32 v50, 0x3db504f3, v50
	s_nop 0
	v_mul_f32_e32 v50, v53, v50
	v_mul_f32_e32 v10, v54, v51
	v_cvt_pk_bf16_f32 v50, v50, v10
	global_store_short v1, v50, s[22:23]
	global_store_short_d16_hi v1, v50, s[22:23] offset:1024
	s_add_u32 s22, s22, 0x1a00
	s_addc_u32 s23, s23, 0
	global_load_ushort v172, v1, s[20:21]
	global_load_ushort v173, v1, s[20:21] offset:1024
	s_add_u32 s20, s20, 0x1a00
	s_addc_u32 s21, s21, 0
	s_waitcnt vmcnt(52)
	v_sub_f32_e32 v52, v83, v96
	v_lshlrev_b32_e32 v50, 16, v174
	v_mul_f32_e32 v52, 0x3fb8aa3b, v52
	v_lshlrev_b32_e32 v51, 16, v175
	v_exp_f32_e32 v53, v52
	v_exp_f32_e64 v54, -v52
	v_mul_f32_e32 v50, 0x3db504f3, v50
	s_nop 0
	v_mul_f32_e32 v50, v53, v50
	v_mul_f32_e32 v11, v54, v51
	v_cvt_pk_bf16_f32 v50, v50, v11
	global_store_short v1, v50, s[22:23]
	global_store_short_d16_hi v1, v50, s[22:23] offset:1024
	s_add_u32 s22, s22, 0x1a00
	s_addc_u32 s23, s23, 0
	global_load_ushort v174, v1, s[20:21]
	global_load_ushort v175, v1, s[20:21] offset:1024
	s_add_u32 s20, s20, 0x1a00
	s_addc_u32 s21, s21, 0
	s_waitcnt vmcnt(52)
	v_sub_f32_e32 v52, v84, v96
	v_lshlrev_b32_e32 v50, 16, v176
	v_mul_f32_e32 v52, 0x3fb8aa3b, v52
	v_lshlrev_b32_e32 v51, 16, v177
	v_exp_f32_e32 v53, v52
	v_exp_f32_e64 v54, -v52
	v_mul_f32_e32 v50, 0x3db504f3, v50
	s_nop 0
	v_mul_f32_e32 v50, v53, v50
	v_mul_f32_e32 v12, v54, v51
	v_cvt_pk_bf16_f32 v50, v50, v12
	global_store_short v1, v50, s[22:23]
	global_store_short_d16_hi v1, v50, s[22:23] offset:1024
	s_add_u32 s22, s22, 0x1a00
	s_addc_u32 s23, s23, 0
	global_load_ushort v176, v1, s[20:21]
	global_load_ushort v177, v1, s[20:21] offset:1024
	s_add_u32 s20, s20, 0x1a00
	s_addc_u32 s21, s21, 0
	s_waitcnt vmcnt(52)
	v_sub_f32_e32 v52, v85, v96
	v_lshlrev_b32_e32 v50, 16, v178
	v_mul_f32_e32 v52, 0x3fb8aa3b, v52
	v_lshlrev_b32_e32 v51, 16, v179
	v_exp_f32_e32 v53, v52
	v_exp_f32_e64 v54, -v52
	v_mul_f32_e32 v50, 0x3db504f3, v50
	s_nop 0
	v_mul_f32_e32 v50, v53, v50
	v_mul_f32_e32 v13, v54, v51
	v_cvt_pk_bf16_f32 v50, v50, v13
	global_store_short v1, v50, s[22:23]
	global_store_short_d16_hi v1, v50, s[22:23] offset:1024
	s_add_u32 s22, s22, 0x1a00
	s_addc_u32 s23, s23, 0
	global_load_ushort v178, v1, s[20:21]
	global_load_ushort v179, v1, s[20:21] offset:1024
	s_add_u32 s20, s20, 0x1a00
	s_addc_u32 s21, s21, 0
	s_waitcnt vmcnt(52)
	v_sub_f32_e32 v52, v86, v96
	v_lshlrev_b32_e32 v50, 16, v180
	v_mul_f32_e32 v52, 0x3fb8aa3b, v52
	v_lshlrev_b32_e32 v51, 16, v181
	v_exp_f32_e32 v53, v52
	v_exp_f32_e64 v54, -v52
	v_mul_f32_e32 v50, 0x3db504f3, v50
	s_nop 0
	v_mul_f32_e32 v50, v53, v50
	v_mul_f32_e32 v14, v54, v51
	v_cvt_pk_bf16_f32 v50, v50, v14
	global_store_short v1, v50, s[22:23]
	global_store_short_d16_hi v1, v50, s[22:23] offset:1024
	s_add_u32 s22, s22, 0x1a00
	s_addc_u32 s23, s23, 0
	global_load_ushort v180, v1, s[20:21]
	global_load_ushort v181, v1, s[20:21] offset:1024
	s_add_u32 s20, s20, 0x1a00
	s_addc_u32 s21, s21, 0
	s_waitcnt vmcnt(52)
	v_sub_f32_e32 v52, v87, v96
	v_lshlrev_b32_e32 v50, 16, v182
	v_mul_f32_e32 v52, 0x3fb8aa3b, v52
	v_lshlrev_b32_e32 v51, 16, v183
	v_exp_f32_e32 v53, v52
	v_exp_f32_e64 v54, -v52
	v_mul_f32_e32 v50, 0x3db504f3, v50
	s_nop 0
	v_mul_f32_e32 v50, v53, v50
	v_mul_f32_e32 v15, v54, v51
	v_cvt_pk_bf16_f32 v50, v50, v15
	global_store_short v1, v50, s[22:23]
	global_store_short_d16_hi v1, v50, s[22:23] offset:1024
	s_add_u32 s22, s22, 0x1a00
	s_addc_u32 s23, s23, 0
	v_cvt_pk_bf16_f32 v4, v8, v9
	v_cvt_pk_bf16_f32 v5, v10, v11
	v_cvt_pk_bf16_f32 v6, v12, v13
	v_cvt_pk_bf16_f32 v7, v14, v15
	global_store_dwordx4 v2, v[4:7], s[26:27] offset:32
	global_load_ushort v182, v1, s[20:21]
	global_load_ushort v183, v1, s[20:21] offset:1024
	s_add_u32 s20, s20, 0x1a00
	s_addc_u32 s21, s21, 0
	s_waitcnt vmcnt(52)
	v_sub_f32_e32 v52, v88, v96
	v_lshlrev_b32_e32 v50, 16, v184
	v_mul_f32_e32 v52, 0x3fb8aa3b, v52
	v_lshlrev_b32_e32 v51, 16, v185
	v_exp_f32_e32 v53, v52
	v_exp_f32_e64 v54, -v52
	v_mul_f32_e32 v50, 0x3db504f3, v50
	s_nop 0
	v_mul_f32_e32 v50, v53, v50
	v_mul_f32_e32 v8, v54, v51
	v_cvt_pk_bf16_f32 v50, v50, v8
	global_store_short v1, v50, s[22:23]
	global_store_short_d16_hi v1, v50, s[22:23] offset:1024
	s_add_u32 s22, s22, 0x1a00
	s_addc_u32 s23, s23, 0
	global_load_ushort v184, v1, s[20:21]
	global_load_ushort v185, v1, s[20:21] offset:1024
	s_add_u32 s20, s20, 0x1a00
	s_addc_u32 s21, s21, 0
	s_waitcnt vmcnt(52)
	v_sub_f32_e32 v52, v89, v96
	v_lshlrev_b32_e32 v50, 16, v186
	v_mul_f32_e32 v52, 0x3fb8aa3b, v52
	v_lshlrev_b32_e32 v51, 16, v187
	v_exp_f32_e32 v53, v52
	v_exp_f32_e64 v54, -v52
	v_mul_f32_e32 v50, 0x3db504f3, v50
	s_nop 0
	v_mul_f32_e32 v50, v53, v50
	v_mul_f32_e32 v9, v54, v51
	v_cvt_pk_bf16_f32 v50, v50, v9
	global_store_short v1, v50, s[22:23]
	global_store_short_d16_hi v1, v50, s[22:23] offset:1024
	s_add_u32 s22, s22, 0x1a00
	s_addc_u32 s23, s23, 0
	global_load_ushort v186, v1, s[20:21]
	global_load_ushort v187, v1, s[20:21] offset:1024
	s_add_u32 s20, s20, 0x1a00
	s_addc_u32 s21, s21, 0
	s_waitcnt vmcnt(52)
	v_sub_f32_e32 v52, v90, v96
	v_lshlrev_b32_e32 v50, 16, v188
	v_mul_f32_e32 v52, 0x3fb8aa3b, v52
	v_lshlrev_b32_e32 v51, 16, v189
	v_exp_f32_e32 v53, v52
	v_exp_f32_e64 v54, -v52
	v_mul_f32_e32 v50, 0x3db504f3, v50
	s_nop 0
	v_mul_f32_e32 v50, v53, v50
	v_mul_f32_e32 v10, v54, v51
	v_cvt_pk_bf16_f32 v50, v50, v10
	global_store_short v1, v50, s[22:23]
	global_store_short_d16_hi v1, v50, s[22:23] offset:1024
	s_add_u32 s22, s22, 0x1a00
	s_addc_u32 s23, s23, 0
	global_load_ushort v188, v1, s[20:21]
	global_load_ushort v189, v1, s[20:21] offset:1024
	s_add_u32 s20, s20, 0x1a00
	s_addc_u32 s21, s21, 0
	s_waitcnt vmcnt(52)
	v_sub_f32_e32 v52, v91, v96
	v_lshlrev_b32_e32 v50, 16, v190
	v_mul_f32_e32 v52, 0x3fb8aa3b, v52
	v_lshlrev_b32_e32 v51, 16, v191
	v_exp_f32_e32 v53, v52
	v_exp_f32_e64 v54, -v52
	v_mul_f32_e32 v50, 0x3db504f3, v50
	s_nop 0
	v_mul_f32_e32 v50, v53, v50
	v_mul_f32_e32 v11, v54, v51
	v_cvt_pk_bf16_f32 v50, v50, v11
	global_store_short v1, v50, s[22:23]
	global_store_short_d16_hi v1, v50, s[22:23] offset:1024
	s_add_u32 s22, s22, 0x1a00
	s_addc_u32 s23, s23, 0
	global_load_ushort v190, v1, s[20:21]
	global_load_ushort v191, v1, s[20:21] offset:1024
	s_add_u32 s20, s20, 0x1a00
	s_addc_u32 s21, s21, 0
	s_waitcnt vmcnt(52)
	v_sub_f32_e32 v52, v92, v96
	v_lshlrev_b32_e32 v50, 16, v192
	v_mul_f32_e32 v52, 0x3fb8aa3b, v52
	v_lshlrev_b32_e32 v51, 16, v193
	v_exp_f32_e32 v53, v52
	v_exp_f32_e64 v54, -v52
	v_mul_f32_e32 v50, 0x3db504f3, v50
	s_nop 0
	v_mul_f32_e32 v50, v53, v50
	v_mul_f32_e32 v12, v54, v51
	v_cvt_pk_bf16_f32 v50, v50, v12
	global_store_short v1, v50, s[22:23]
	global_store_short_d16_hi v1, v50, s[22:23] offset:1024
	s_add_u32 s22, s22, 0x1a00
	s_addc_u32 s23, s23, 0
	global_load_ushort v192, v1, s[20:21]
	global_load_ushort v193, v1, s[20:21] offset:1024
	s_add_u32 s20, s20, 0x1a00
	s_addc_u32 s21, s21, 0
	s_waitcnt vmcnt(52)
	v_sub_f32_e32 v52, v93, v96
	v_lshlrev_b32_e32 v50, 16, v194
	v_mul_f32_e32 v52, 0x3fb8aa3b, v52
	v_lshlrev_b32_e32 v51, 16, v195
	v_exp_f32_e32 v53, v52
	v_exp_f32_e64 v54, -v52
	v_mul_f32_e32 v50, 0x3db504f3, v50
	s_nop 0
	v_mul_f32_e32 v50, v53, v50
	v_mul_f32_e32 v13, v54, v51
	v_cvt_pk_bf16_f32 v50, v50, v13
	global_store_short v1, v50, s[22:23]
	global_store_short_d16_hi v1, v50, s[22:23] offset:1024
	s_add_u32 s22, s22, 0x1a00
	s_addc_u32 s23, s23, 0
	global_load_ushort v194, v1, s[20:21]
	global_load_ushort v195, v1, s[20:21] offset:1024
	s_add_u32 s20, s20, 0x1a00
	s_addc_u32 s21, s21, 0
	s_waitcnt vmcnt(52)
	v_sub_f32_e32 v52, v94, v96
	v_lshlrev_b32_e32 v50, 16, v196
	v_mul_f32_e32 v52, 0x3fb8aa3b, v52
	v_lshlrev_b32_e32 v51, 16, v197
	v_exp_f32_e32 v53, v52
	v_exp_f32_e64 v54, -v52
	v_mul_f32_e32 v50, 0x3db504f3, v50
	s_nop 0
	v_mul_f32_e32 v50, v53, v50
	v_mul_f32_e32 v14, v54, v51
	v_cvt_pk_bf16_f32 v50, v50, v14
	global_store_short v1, v50, s[22:23]
	global_store_short_d16_hi v1, v50, s[22:23] offset:1024
	s_add_u32 s22, s22, 0x1a00
	s_addc_u32 s23, s23, 0
	global_load_ushort v196, v1, s[20:21]
	global_load_ushort v197, v1, s[20:21] offset:1024
	s_add_u32 s20, s20, 0x1a00
	s_addc_u32 s21, s21, 0
	s_waitcnt vmcnt(52)
	v_sub_f32_e32 v52, v95, v96
	v_lshlrev_b32_e32 v50, 16, v198
	v_mul_f32_e32 v52, 0x3fb8aa3b, v52
	v_lshlrev_b32_e32 v51, 16, v199
	v_exp_f32_e32 v53, v52
	v_exp_f32_e64 v54, -v52
	v_mul_f32_e32 v50, 0x3db504f3, v50
	s_nop 0
	v_mul_f32_e32 v50, v53, v50
	v_mul_f32_e32 v15, v54, v51
	v_cvt_pk_bf16_f32 v50, v50, v15
	global_store_short v1, v50, s[22:23]
	global_store_short_d16_hi v1, v50, s[22:23] offset:1024
	s_add_u32 s22, s22, 0x1a00
	s_addc_u32 s23, s23, 0
	v_cvt_pk_bf16_f32 v4, v8, v9
	v_cvt_pk_bf16_f32 v5, v10, v11
	v_cvt_pk_bf16_f32 v6, v12, v13
	v_cvt_pk_bf16_f32 v7, v14, v15
	global_store_dwordx4 v2, v[4:7], s[26:27] offset:48
	global_load_ushort v198, v1, s[20:21]
	global_load_ushort v199, v1, s[20:21] offset:1024
	s_add_u32 s20, s20, 0x1a00
	s_addc_u32 s21, s21, 0
	s_waitcnt lgkmcnt(0)
	ds_read_b128 v[34:37], v3 offset:2304
	ds_read_b128 v[38:41], v3 offset:2320
	ds_read_b128 v[42:45], v3 offset:2336
	ds_read_b128 v[46:49], v3 offset:2352
	ds_read_b128 v[200:203], v3 offset:2368
	ds_read_b128 v[204:207], v3 offset:2384
	ds_read_b128 v[208:211], v3 offset:2400
	ds_read_b128 v[212:215], v3 offset:2416
	v_fma_f32 v50, v16, v216, v32
	v_fma_f32 v51, v16, v236, v32
	v_fmac_f32_e32 v50, v17, v217
	v_fmac_f32_e32 v51, v17, v237
	v_fmac_f32_e32 v50, v18, v218
	v_fmac_f32_e32 v51, v18, v238
	v_fmac_f32_e32 v50, v19, v219
	v_fmac_f32_e32 v51, v19, v239
	v_fmac_f32_e32 v50, v20, v220
	v_fmac_f32_e32 v51, v20, v240
	v_fmac_f32_e32 v50, v21, v221
	v_fmac_f32_e32 v51, v21, v241
	v_fmac_f32_e32 v50, v22, v222
	v_fmac_f32_e32 v51, v22, v242
	v_fmac_f32_e32 v50, v23, v223
	v_fmac_f32_e32 v51, v23, v243
	v_fmac_f32_e32 v50, v24, v224
	v_fmac_f32_e32 v51, v24, v244
	v_fmac_f32_e32 v50, v25, v225
	v_fmac_f32_e32 v51, v25, v245
	v_fmac_f32_e32 v50, v26, v226
	v_fmac_f32_e32 v51, v26, v246
	v_fmac_f32_e32 v50, v27, v227
	v_fmac_f32_e32 v51, v27, v247
	v_fmac_f32_e32 v50, v28, v232
	v_fmac_f32_e32 v51, v28, v248
	v_fmac_f32_e32 v50, v29, v233
	v_fmac_f32_e32 v51, v29, v249
	v_fmac_f32_e32 v50, v30, v234
	v_fmac_f32_e32 v51, v30, v250
	v_fmac_f32_e32 v50, v31, v235
	v_fmac_f32_e32 v51, v31, v251
	v_mul_f32_e64 v52, |v50|, s7
	v_mul_f32_e64 v53, |v51|, s7
	v_exp_f32_e32 v52, v52
	v_exp_f32_e32 v53, v53
	v_min_f32_e32 v50, 0, v50
	v_add_f32_e32 v52, 1.0, v52
	v_add_f32_e32 v53, 1.0, v53
	v_log_f32_e32 v52, v52
	v_log_f32_e32 v53, v53
	v_min_f32_e32 v51, 0, v51
	v_mul_f32_e32 v54, 0x3f317217, v52
	v_mul_f32_e32 v55, 0x3f317217, v53
	v_fma_f32 v56, v52, s9, -v54
	v_fma_f32 v57, v53, s9, -v55
	v_fmac_f32_e32 v56, 0x3377d1cf, v52
	v_fmac_f32_e32 v57, 0x3377d1cf, v53
	v_add_f32_e32 v54, v54, v56
	v_add_f32_e32 v55, v55, v57
	v_sub_f32_e32 v50, v50, v54
	v_sub_f32_e32 v51, v51, v55
	v_fmamk_f32 v98, v50, 0x3d800000, v97
	v_fmamk_f32 v99, v51, 0x3d800000, v98
	s_waitcnt lgkmcnt(0)
	ds_read_b128 v[216:219], v3 offset:2432
	ds_read_b128 v[220:223], v3 offset:2448
	ds_read_b128 v[224:227], v3 offset:2464
	ds_read_b128 v[232:235], v3 offset:2480
	ds_read_b128 v[236:239], v3 offset:2496
	ds_read_b128 v[240:243], v3 offset:2512
	ds_read_b128 v[244:247], v3 offset:2528
	ds_read_b128 v[248:251], v3 offset:2544
	v_fma_f32 v50, v16, v34, v32
	v_fma_f32 v51, v16, v200, v32
	v_fmac_f32_e32 v50, v17, v35
	v_fmac_f32_e32 v51, v17, v201
	v_fmac_f32_e32 v50, v18, v36
	v_fmac_f32_e32 v51, v18, v202
	v_fmac_f32_e32 v50, v19, v37
	v_fmac_f32_e32 v51, v19, v203
	v_fmac_f32_e32 v50, v20, v38
	v_fmac_f32_e32 v51, v20, v204
	v_fmac_f32_e32 v50, v21, v39
	v_fmac_f32_e32 v51, v21, v205
	v_fmac_f32_e32 v50, v22, v40
	v_fmac_f32_e32 v51, v22, v206
	v_fmac_f32_e32 v50, v23, v41
	v_fmac_f32_e32 v51, v23, v207
	v_fmac_f32_e32 v50, v24, v42
	v_fmac_f32_e32 v51, v24, v208
	v_fmac_f32_e32 v50, v25, v43
	v_fmac_f32_e32 v51, v25, v209
	v_fmac_f32_e32 v50, v26, v44
	v_fmac_f32_e32 v51, v26, v210
	v_fmac_f32_e32 v50, v27, v45
	v_fmac_f32_e32 v51, v27, v211
	v_fmac_f32_e32 v50, v28, v46
	v_fmac_f32_e32 v51, v28, v212
	v_fmac_f32_e32 v50, v29, v47
	v_fmac_f32_e32 v51, v29, v213
	v_fmac_f32_e32 v50, v30, v48
	v_fmac_f32_e32 v51, v30, v214
	v_fmac_f32_e32 v50, v31, v49
	v_fmac_f32_e32 v51, v31, v215
	v_mul_f32_e64 v52, |v50|, s7
	v_mul_f32_e64 v53, |v51|, s7
	v_exp_f32_e32 v52, v52
	v_exp_f32_e32 v53, v53
	v_min_f32_e32 v50, 0, v50
	v_add_f32_e32 v52, 1.0, v52
	v_add_f32_e32 v53, 1.0, v53
	v_log_f32_e32 v52, v52
	v_log_f32_e32 v53, v53
	v_min_f32_e32 v51, 0, v51
	v_mul_f32_e32 v54, 0x3f317217, v52
	v_mul_f32_e32 v55, 0x3f317217, v53
	v_fma_f32 v56, v52, s9, -v54
	v_fma_f32 v57, v53, s9, -v55
	v_fmac_f32_e32 v56, 0x3377d1cf, v52
	v_fmac_f32_e32 v57, 0x3377d1cf, v53
	v_add_f32_e32 v54, v54, v56
	v_add_f32_e32 v55, v55, v57
	v_sub_f32_e32 v50, v50, v54
	v_sub_f32_e32 v51, v51, v55
	v_fmamk_f32 v100, v50, 0x3d800000, v99
	v_fmamk_f32 v101, v51, 0x3d800000, v100
	s_waitcnt lgkmcnt(0)
	ds_read_b128 v[34:37], v3 offset:2560
	ds_read_b128 v[38:41], v3 offset:2576
	ds_read_b128 v[42:45], v3 offset:2592
	ds_read_b128 v[46:49], v3 offset:2608
	ds_read_b128 v[200:203], v3 offset:2624
	ds_read_b128 v[204:207], v3 offset:2640
	ds_read_b128 v[208:211], v3 offset:2656
	ds_read_b128 v[212:215], v3 offset:2672
	v_fma_f32 v50, v16, v216, v32
	v_fma_f32 v51, v16, v236, v32
	v_fmac_f32_e32 v50, v17, v217
	v_fmac_f32_e32 v51, v17, v237
	v_fmac_f32_e32 v50, v18, v218
	v_fmac_f32_e32 v51, v18, v238
	v_fmac_f32_e32 v50, v19, v219
	v_fmac_f32_e32 v51, v19, v239
	v_fmac_f32_e32 v50, v20, v220
	v_fmac_f32_e32 v51, v20, v240
	v_fmac_f32_e32 v50, v21, v221
	v_fmac_f32_e32 v51, v21, v241
	v_fmac_f32_e32 v50, v22, v222
	v_fmac_f32_e32 v51, v22, v242
	v_fmac_f32_e32 v50, v23, v223
	v_fmac_f32_e32 v51, v23, v243
	v_fmac_f32_e32 v50, v24, v224
	v_fmac_f32_e32 v51, v24, v244
	v_fmac_f32_e32 v50, v25, v225
	v_fmac_f32_e32 v51, v25, v245
	v_fmac_f32_e32 v50, v26, v226
	v_fmac_f32_e32 v51, v26, v246
	v_fmac_f32_e32 v50, v27, v227
	v_fmac_f32_e32 v51, v27, v247
	v_fmac_f32_e32 v50, v28, v232
	v_fmac_f32_e32 v51, v28, v248
	v_fmac_f32_e32 v50, v29, v233
	v_fmac_f32_e32 v51, v29, v249
	v_fmac_f32_e32 v50, v30, v234
	v_fmac_f32_e32 v51, v30, v250
	v_fmac_f32_e32 v50, v31, v235
	v_fmac_f32_e32 v51, v31, v251
	v_mul_f32_e64 v52, |v50|, s7
	v_mul_f32_e64 v53, |v51|, s7
	v_exp_f32_e32 v52, v52
	v_exp_f32_e32 v53, v53
	v_min_f32_e32 v50, 0, v50
	v_add_f32_e32 v52, 1.0, v52
	v_add_f32_e32 v53, 1.0, v53
	v_log_f32_e32 v52, v52
	v_log_f32_e32 v53, v53
	v_min_f32_e32 v51, 0, v51
	v_mul_f32_e32 v54, 0x3f317217, v52
	v_mul_f32_e32 v55, 0x3f317217, v53
	v_fma_f32 v56, v52, s9, -v54
	v_fma_f32 v57, v53, s9, -v55
	v_fmac_f32_e32 v56, 0x3377d1cf, v52
	v_fmac_f32_e32 v57, 0x3377d1cf, v53
	v_add_f32_e32 v54, v54, v56
	v_add_f32_e32 v55, v55, v57
	v_sub_f32_e32 v50, v50, v54
	v_sub_f32_e32 v51, v51, v55
	v_fmamk_f32 v102, v50, 0x3d800000, v101
	v_fmamk_f32 v103, v51, 0x3d800000, v102
	s_waitcnt lgkmcnt(0)
	ds_read_b128 v[216:219], v3 offset:2688
	ds_read_b128 v[220:223], v3 offset:2704
	ds_read_b128 v[224:227], v3 offset:2720
	ds_read_b128 v[232:235], v3 offset:2736
	ds_read_b128 v[236:239], v3 offset:2752
	ds_read_b128 v[240:243], v3 offset:2768
	ds_read_b128 v[244:247], v3 offset:2784
	ds_read_b128 v[248:251], v3 offset:2800
	v_fma_f32 v50, v16, v34, v32
	v_fma_f32 v51, v16, v200, v32
	v_fmac_f32_e32 v50, v17, v35
	v_fmac_f32_e32 v51, v17, v201
	v_fmac_f32_e32 v50, v18, v36
	v_fmac_f32_e32 v51, v18, v202
	v_fmac_f32_e32 v50, v19, v37
	v_fmac_f32_e32 v51, v19, v203
	v_fmac_f32_e32 v50, v20, v38
	v_fmac_f32_e32 v51, v20, v204
	v_fmac_f32_e32 v50, v21, v39
	v_fmac_f32_e32 v51, v21, v205
	v_fmac_f32_e32 v50, v22, v40
	v_fmac_f32_e32 v51, v22, v206
	v_fmac_f32_e32 v50, v23, v41
	v_fmac_f32_e32 v51, v23, v207
	v_fmac_f32_e32 v50, v24, v42
	v_fmac_f32_e32 v51, v24, v208
	v_fmac_f32_e32 v50, v25, v43
	v_fmac_f32_e32 v51, v25, v209
	v_fmac_f32_e32 v50, v26, v44
	v_fmac_f32_e32 v51, v26, v210
	v_fmac_f32_e32 v50, v27, v45
	v_fmac_f32_e32 v51, v27, v211
	v_fmac_f32_e32 v50, v28, v46
	v_fmac_f32_e32 v51, v28, v212
	v_fmac_f32_e32 v50, v29, v47
	v_fmac_f32_e32 v51, v29, v213
	v_fmac_f32_e32 v50, v30, v48
	v_fmac_f32_e32 v51, v30, v214
	v_fmac_f32_e32 v50, v31, v49
	v_fmac_f32_e32 v51, v31, v215
	v_mul_f32_e64 v52, |v50|, s7
	v_mul_f32_e64 v53, |v51|, s7
	v_exp_f32_e32 v52, v52
	v_exp_f32_e32 v53, v53
	v_min_f32_e32 v50, 0, v50
	v_add_f32_e32 v52, 1.0, v52
	v_add_f32_e32 v53, 1.0, v53
	v_log_f32_e32 v52, v52
	v_log_f32_e32 v53, v53
	v_min_f32_e32 v51, 0, v51
	v_mul_f32_e32 v54, 0x3f317217, v52
	v_mul_f32_e32 v55, 0x3f317217, v53
	v_fma_f32 v56, v52, s9, -v54
	v_fma_f32 v57, v53, s9, -v55
	v_fmac_f32_e32 v56, 0x3377d1cf, v52
	v_fmac_f32_e32 v57, 0x3377d1cf, v53
	v_add_f32_e32 v54, v54, v56
	v_add_f32_e32 v55, v55, v57
	v_sub_f32_e32 v50, v50, v54
	v_sub_f32_e32 v51, v51, v55
	v_fmamk_f32 v104, v50, 0x3d800000, v103
	v_fmamk_f32 v105, v51, 0x3d800000, v104
	s_waitcnt lgkmcnt(0)
	ds_read_b128 v[34:37], v3 offset:2816
	ds_read_b128 v[38:41], v3 offset:2832
	ds_read_b128 v[42:45], v3 offset:2848
	ds_read_b128 v[46:49], v3 offset:2864
	ds_read_b128 v[200:203], v3 offset:2880
	ds_read_b128 v[204:207], v3 offset:2896
	ds_read_b128 v[208:211], v3 offset:2912
	ds_read_b128 v[212:215], v3 offset:2928
	v_fma_f32 v50, v16, v216, v32
	v_fma_f32 v51, v16, v236, v32
	v_fmac_f32_e32 v50, v17, v217
	v_fmac_f32_e32 v51, v17, v237
	v_fmac_f32_e32 v50, v18, v218
	v_fmac_f32_e32 v51, v18, v238
	v_fmac_f32_e32 v50, v19, v219
	v_fmac_f32_e32 v51, v19, v239
	v_fmac_f32_e32 v50, v20, v220
	v_fmac_f32_e32 v51, v20, v240
	v_fmac_f32_e32 v50, v21, v221
	v_fmac_f32_e32 v51, v21, v241
	v_fmac_f32_e32 v50, v22, v222
	v_fmac_f32_e32 v51, v22, v242
	v_fmac_f32_e32 v50, v23, v223
	v_fmac_f32_e32 v51, v23, v243
	v_fmac_f32_e32 v50, v24, v224
	v_fmac_f32_e32 v51, v24, v244
	v_fmac_f32_e32 v50, v25, v225
	v_fmac_f32_e32 v51, v25, v245
	v_fmac_f32_e32 v50, v26, v226
	v_fmac_f32_e32 v51, v26, v246
	v_fmac_f32_e32 v50, v27, v227
	v_fmac_f32_e32 v51, v27, v247
	v_fmac_f32_e32 v50, v28, v232
	v_fmac_f32_e32 v51, v28, v248
	v_fmac_f32_e32 v50, v29, v233
	v_fmac_f32_e32 v51, v29, v249
	v_fmac_f32_e32 v50, v30, v234
	v_fmac_f32_e32 v51, v30, v250
	v_fmac_f32_e32 v50, v31, v235
	v_fmac_f32_e32 v51, v31, v251
	v_mul_f32_e64 v52, |v50|, s7
	v_mul_f32_e64 v53, |v51|, s7
	v_exp_f32_e32 v52, v52
	v_exp_f32_e32 v53, v53
	v_min_f32_e32 v50, 0, v50
	v_add_f32_e32 v52, 1.0, v52
	v_add_f32_e32 v53, 1.0, v53
	v_log_f32_e32 v52, v52
	v_log_f32_e32 v53, v53
	v_min_f32_e32 v51, 0, v51
	v_mul_f32_e32 v54, 0x3f317217, v52
	v_mul_f32_e32 v55, 0x3f317217, v53
	v_fma_f32 v56, v52, s9, -v54
	v_fma_f32 v57, v53, s9, -v55
	v_fmac_f32_e32 v56, 0x3377d1cf, v52
	v_fmac_f32_e32 v57, 0x3377d1cf, v53
	v_add_f32_e32 v54, v54, v56
	v_add_f32_e32 v55, v55, v57
	v_sub_f32_e32 v50, v50, v54
	v_sub_f32_e32 v51, v51, v55
	v_fmamk_f32 v106, v50, 0x3d800000, v105
	v_fmamk_f32 v107, v51, 0x3d800000, v106
	s_waitcnt lgkmcnt(0)
	ds_read_b128 v[216:219], v3 offset:2944
	ds_read_b128 v[220:223], v3 offset:2960
	ds_read_b128 v[224:227], v3 offset:2976
	ds_read_b128 v[232:235], v3 offset:2992
	ds_read_b128 v[236:239], v3 offset:3008
	ds_read_b128 v[240:243], v3 offset:3024
	ds_read_b128 v[244:247], v3 offset:3040
	ds_read_b128 v[248:251], v3 offset:3056
	v_fma_f32 v50, v16, v34, v32
	v_fma_f32 v51, v16, v200, v32
	v_fmac_f32_e32 v50, v17, v35
	v_fmac_f32_e32 v51, v17, v201
	v_fmac_f32_e32 v50, v18, v36
	v_fmac_f32_e32 v51, v18, v202
	v_fmac_f32_e32 v50, v19, v37
	v_fmac_f32_e32 v51, v19, v203
	v_fmac_f32_e32 v50, v20, v38
	v_fmac_f32_e32 v51, v20, v204
	v_fmac_f32_e32 v50, v21, v39
	v_fmac_f32_e32 v51, v21, v205
	v_fmac_f32_e32 v50, v22, v40
	v_fmac_f32_e32 v51, v22, v206
	v_fmac_f32_e32 v50, v23, v41
	v_fmac_f32_e32 v51, v23, v207
	v_fmac_f32_e32 v50, v24, v42
	v_fmac_f32_e32 v51, v24, v208
	v_fmac_f32_e32 v50, v25, v43
	v_fmac_f32_e32 v51, v25, v209
	v_fmac_f32_e32 v50, v26, v44
	v_fmac_f32_e32 v51, v26, v210
	v_fmac_f32_e32 v50, v27, v45
	v_fmac_f32_e32 v51, v27, v211
	v_fmac_f32_e32 v50, v28, v46
	v_fmac_f32_e32 v51, v28, v212
	v_fmac_f32_e32 v50, v29, v47
	v_fmac_f32_e32 v51, v29, v213
	v_fmac_f32_e32 v50, v30, v48
	v_fmac_f32_e32 v51, v30, v214
	v_fmac_f32_e32 v50, v31, v49
	v_fmac_f32_e32 v51, v31, v215
	v_mul_f32_e64 v52, |v50|, s7
	v_mul_f32_e64 v53, |v51|, s7
	v_exp_f32_e32 v52, v52
	v_exp_f32_e32 v53, v53
	v_min_f32_e32 v50, 0, v50
	v_add_f32_e32 v52, 1.0, v52
	v_add_f32_e32 v53, 1.0, v53
	v_log_f32_e32 v52, v52
	v_log_f32_e32 v53, v53
	v_min_f32_e32 v51, 0, v51
	v_mul_f32_e32 v54, 0x3f317217, v52
	v_mul_f32_e32 v55, 0x3f317217, v53
	v_fma_f32 v56, v52, s9, -v54
	v_fma_f32 v57, v53, s9, -v55
	v_fmac_f32_e32 v56, 0x3377d1cf, v52
	v_fmac_f32_e32 v57, 0x3377d1cf, v53
	v_add_f32_e32 v54, v54, v56
	v_add_f32_e32 v55, v55, v57
	v_sub_f32_e32 v50, v50, v54
	v_sub_f32_e32 v51, v51, v55
	v_fmamk_f32 v108, v50, 0x3d800000, v107
	v_fmamk_f32 v109, v51, 0x3d800000, v108
	s_waitcnt lgkmcnt(0)
	ds_read_b128 v[34:37], v3 offset:3072
	ds_read_b128 v[38:41], v3 offset:3088
	ds_read_b128 v[42:45], v3 offset:3104
	ds_read_b128 v[46:49], v3 offset:3120
	ds_read_b128 v[200:203], v3 offset:3136
	ds_read_b128 v[204:207], v3 offset:3152
	ds_read_b128 v[208:211], v3 offset:3168
	ds_read_b128 v[212:215], v3 offset:3184
	v_fma_f32 v50, v16, v216, v32
	v_fma_f32 v51, v16, v236, v32
	v_fmac_f32_e32 v50, v17, v217
	v_fmac_f32_e32 v51, v17, v237
	v_fmac_f32_e32 v50, v18, v218
	v_fmac_f32_e32 v51, v18, v238
	v_fmac_f32_e32 v50, v19, v219
	v_fmac_f32_e32 v51, v19, v239
	v_fmac_f32_e32 v50, v20, v220
	v_fmac_f32_e32 v51, v20, v240
	v_fmac_f32_e32 v50, v21, v221
	v_fmac_f32_e32 v51, v21, v241
	v_fmac_f32_e32 v50, v22, v222
	v_fmac_f32_e32 v51, v22, v242
	v_fmac_f32_e32 v50, v23, v223
	v_fmac_f32_e32 v51, v23, v243
	v_fmac_f32_e32 v50, v24, v224
	v_fmac_f32_e32 v51, v24, v244
	v_fmac_f32_e32 v50, v25, v225
	v_fmac_f32_e32 v51, v25, v245
	v_fmac_f32_e32 v50, v26, v226
	v_fmac_f32_e32 v51, v26, v246
	v_fmac_f32_e32 v50, v27, v227
	v_fmac_f32_e32 v51, v27, v247
	v_fmac_f32_e32 v50, v28, v232
	v_fmac_f32_e32 v51, v28, v248
	v_fmac_f32_e32 v50, v29, v233
	v_fmac_f32_e32 v51, v29, v249
	v_fmac_f32_e32 v50, v30, v234
	v_fmac_f32_e32 v51, v30, v250
	v_fmac_f32_e32 v50, v31, v235
	v_fmac_f32_e32 v51, v31, v251
	v_mul_f32_e64 v52, |v50|, s7
	v_mul_f32_e64 v53, |v51|, s7
	v_exp_f32_e32 v52, v52
	v_exp_f32_e32 v53, v53
	v_min_f32_e32 v50, 0, v50
	v_add_f32_e32 v52, 1.0, v52
	v_add_f32_e32 v53, 1.0, v53
	v_log_f32_e32 v52, v52
	v_log_f32_e32 v53, v53
	v_min_f32_e32 v51, 0, v51
	v_mul_f32_e32 v54, 0x3f317217, v52
	v_mul_f32_e32 v55, 0x3f317217, v53
	v_fma_f32 v56, v52, s9, -v54
	v_fma_f32 v57, v53, s9, -v55
	v_fmac_f32_e32 v56, 0x3377d1cf, v52
	v_fmac_f32_e32 v57, 0x3377d1cf, v53
	v_add_f32_e32 v54, v54, v56
	v_add_f32_e32 v55, v55, v57
	v_sub_f32_e32 v50, v50, v54
	v_sub_f32_e32 v51, v51, v55
	v_fmamk_f32 v110, v50, 0x3d800000, v109
	v_fmamk_f32 v111, v51, 0x3d800000, v110
	s_waitcnt lgkmcnt(0)
	ds_read_b128 v[216:219], v3 offset:3200
	ds_read_b128 v[220:223], v3 offset:3216
	ds_read_b128 v[224:227], v3 offset:3232
	ds_read_b128 v[232:235], v3 offset:3248
	ds_read_b128 v[236:239], v3 offset:3264
	ds_read_b128 v[240:243], v3 offset:3280
	ds_read_b128 v[244:247], v3 offset:3296
	ds_read_b128 v[248:251], v3 offset:3312
	v_fma_f32 v50, v16, v34, v32
	v_fma_f32 v51, v16, v200, v32
	v_fmac_f32_e32 v50, v17, v35
	v_fmac_f32_e32 v51, v17, v201
	v_fmac_f32_e32 v50, v18, v36
	v_fmac_f32_e32 v51, v18, v202
	v_fmac_f32_e32 v50, v19, v37
	v_fmac_f32_e32 v51, v19, v203
	v_fmac_f32_e32 v50, v20, v38
	v_fmac_f32_e32 v51, v20, v204
	v_fmac_f32_e32 v50, v21, v39
	v_fmac_f32_e32 v51, v21, v205
	v_fmac_f32_e32 v50, v22, v40
	v_fmac_f32_e32 v51, v22, v206
	v_fmac_f32_e32 v50, v23, v41
	v_fmac_f32_e32 v51, v23, v207
	v_fmac_f32_e32 v50, v24, v42
	v_fmac_f32_e32 v51, v24, v208
	v_fmac_f32_e32 v50, v25, v43
	v_fmac_f32_e32 v51, v25, v209
	v_fmac_f32_e32 v50, v26, v44
	v_fmac_f32_e32 v51, v26, v210
	v_fmac_f32_e32 v50, v27, v45
	v_fmac_f32_e32 v51, v27, v211
	v_fmac_f32_e32 v50, v28, v46
	v_fmac_f32_e32 v51, v28, v212
	v_fmac_f32_e32 v50, v29, v47
	v_fmac_f32_e32 v51, v29, v213
	v_fmac_f32_e32 v50, v30, v48
	v_fmac_f32_e32 v51, v30, v214
	v_fmac_f32_e32 v50, v31, v49
	v_fmac_f32_e32 v51, v31, v215
	v_mul_f32_e64 v52, |v50|, s7
	v_mul_f32_e64 v53, |v51|, s7
	v_exp_f32_e32 v52, v52
	v_exp_f32_e32 v53, v53
	v_min_f32_e32 v50, 0, v50
	v_add_f32_e32 v52, 1.0, v52
	v_add_f32_e32 v53, 1.0, v53
	v_log_f32_e32 v52, v52
	v_log_f32_e32 v53, v53
	v_min_f32_e32 v51, 0, v51
	v_mul_f32_e32 v54, 0x3f317217, v52
	v_mul_f32_e32 v55, 0x3f317217, v53
	v_fma_f32 v56, v52, s9, -v54
	v_fma_f32 v57, v53, s9, -v55
	v_fmac_f32_e32 v56, 0x3377d1cf, v52
	v_fmac_f32_e32 v57, 0x3377d1cf, v53
	v_add_f32_e32 v54, v54, v56
	v_add_f32_e32 v55, v55, v57
	v_sub_f32_e32 v50, v50, v54
	v_sub_f32_e32 v51, v51, v55
	v_fmamk_f32 v112, v50, 0x3d800000, v111
	v_fmamk_f32 v113, v51, 0x3d800000, v112
	s_waitcnt lgkmcnt(0)
	ds_read_b128 v[34:37], v3 offset:3328
	ds_read_b128 v[38:41], v3 offset:3344
	ds_read_b128 v[42:45], v3 offset:3360
	ds_read_b128 v[46:49], v3 offset:3376
	ds_read_b128 v[200:203], v3 offset:3392
	ds_read_b128 v[204:207], v3 offset:3408
	ds_read_b128 v[208:211], v3 offset:3424
	ds_read_b128 v[212:215], v3 offset:3440
	v_fma_f32 v50, v16, v216, v32
	v_fma_f32 v51, v16, v236, v32
	v_fmac_f32_e32 v50, v17, v217
	v_fmac_f32_e32 v51, v17, v237
	v_fmac_f32_e32 v50, v18, v218
	v_fmac_f32_e32 v51, v18, v238
	v_fmac_f32_e32 v50, v19, v219
	v_fmac_f32_e32 v51, v19, v239
	v_fmac_f32_e32 v50, v20, v220
	v_fmac_f32_e32 v51, v20, v240
	v_fmac_f32_e32 v50, v21, v221
	v_fmac_f32_e32 v51, v21, v241
	v_fmac_f32_e32 v50, v22, v222
	v_fmac_f32_e32 v51, v22, v242
	v_fmac_f32_e32 v50, v23, v223
	v_fmac_f32_e32 v51, v23, v243
	v_fmac_f32_e32 v50, v24, v224
	v_fmac_f32_e32 v51, v24, v244
	v_fmac_f32_e32 v50, v25, v225
	v_fmac_f32_e32 v51, v25, v245
	v_fmac_f32_e32 v50, v26, v226
	v_fmac_f32_e32 v51, v26, v246
	v_fmac_f32_e32 v50, v27, v227
	v_fmac_f32_e32 v51, v27, v247
	v_fmac_f32_e32 v50, v28, v232
	v_fmac_f32_e32 v51, v28, v248
	v_fmac_f32_e32 v50, v29, v233
	v_fmac_f32_e32 v51, v29, v249
	v_fmac_f32_e32 v50, v30, v234
	v_fmac_f32_e32 v51, v30, v250
	v_fmac_f32_e32 v50, v31, v235
	v_fmac_f32_e32 v51, v31, v251
	v_mul_f32_e64 v52, |v50|, s7
	v_mul_f32_e64 v53, |v51|, s7
	v_exp_f32_e32 v52, v52
	v_exp_f32_e32 v53, v53
	v_min_f32_e32 v50, 0, v50
	v_add_f32_e32 v52, 1.0, v52
	v_add_f32_e32 v53, 1.0, v53
	v_log_f32_e32 v52, v52
	v_log_f32_e32 v53, v53
	v_min_f32_e32 v51, 0, v51
	v_mul_f32_e32 v54, 0x3f317217, v52
	v_mul_f32_e32 v55, 0x3f317217, v53
	v_fma_f32 v56, v52, s9, -v54
	v_fma_f32 v57, v53, s9, -v55
	v_fmac_f32_e32 v56, 0x3377d1cf, v52
	v_fmac_f32_e32 v57, 0x3377d1cf, v53
	v_add_f32_e32 v54, v54, v56
	v_add_f32_e32 v55, v55, v57
	v_sub_f32_e32 v50, v50, v54
	v_sub_f32_e32 v51, v51, v55
	v_fmamk_f32 v114, v50, 0x3d800000, v113
	v_fmamk_f32 v115, v51, 0x3d800000, v114
	s_waitcnt lgkmcnt(0)
	ds_read_b128 v[216:219], v3 offset:3456
	ds_read_b128 v[220:223], v3 offset:3472
	ds_read_b128 v[224:227], v3 offset:3488
	ds_read_b128 v[232:235], v3 offset:3504
	ds_read_b128 v[236:239], v3 offset:3520
	ds_read_b128 v[240:243], v3 offset:3536
	ds_read_b128 v[244:247], v3 offset:3552
	ds_read_b128 v[248:251], v3 offset:3568
	v_fma_f32 v50, v16, v34, v32
	v_fma_f32 v51, v16, v200, v32
	v_fmac_f32_e32 v50, v17, v35
	v_fmac_f32_e32 v51, v17, v201
	v_fmac_f32_e32 v50, v18, v36
	v_fmac_f32_e32 v51, v18, v202
	v_fmac_f32_e32 v50, v19, v37
	v_fmac_f32_e32 v51, v19, v203
	v_fmac_f32_e32 v50, v20, v38
	v_fmac_f32_e32 v51, v20, v204
	v_fmac_f32_e32 v50, v21, v39
	v_fmac_f32_e32 v51, v21, v205
	v_fmac_f32_e32 v50, v22, v40
	v_fmac_f32_e32 v51, v22, v206
	v_fmac_f32_e32 v50, v23, v41
	v_fmac_f32_e32 v51, v23, v207
	v_fmac_f32_e32 v50, v24, v42
	v_fmac_f32_e32 v51, v24, v208
	v_fmac_f32_e32 v50, v25, v43
	v_fmac_f32_e32 v51, v25, v209
	v_fmac_f32_e32 v50, v26, v44
	v_fmac_f32_e32 v51, v26, v210
	v_fmac_f32_e32 v50, v27, v45
	v_fmac_f32_e32 v51, v27, v211
	v_fmac_f32_e32 v50, v28, v46
	v_fmac_f32_e32 v51, v28, v212
	v_fmac_f32_e32 v50, v29, v47
	v_fmac_f32_e32 v51, v29, v213
	v_fmac_f32_e32 v50, v30, v48
	v_fmac_f32_e32 v51, v30, v214
	v_fmac_f32_e32 v50, v31, v49
	v_fmac_f32_e32 v51, v31, v215
	v_mul_f32_e64 v52, |v50|, s7
	v_mul_f32_e64 v53, |v51|, s7
	v_exp_f32_e32 v52, v52
	v_exp_f32_e32 v53, v53
	v_min_f32_e32 v50, 0, v50
	v_add_f32_e32 v52, 1.0, v52
	v_add_f32_e32 v53, 1.0, v53
	v_log_f32_e32 v52, v52
	v_log_f32_e32 v53, v53
	v_min_f32_e32 v51, 0, v51
	v_mul_f32_e32 v54, 0x3f317217, v52
	v_mul_f32_e32 v55, 0x3f317217, v53
	v_fma_f32 v56, v52, s9, -v54
	v_fma_f32 v57, v53, s9, -v55
	v_fmac_f32_e32 v56, 0x3377d1cf, v52
	v_fmac_f32_e32 v57, 0x3377d1cf, v53
	v_add_f32_e32 v54, v54, v56
	v_add_f32_e32 v55, v55, v57
	v_sub_f32_e32 v50, v50, v54
	v_sub_f32_e32 v51, v51, v55
	v_fmamk_f32 v116, v50, 0x3d800000, v115
	v_fmamk_f32 v117, v51, 0x3d800000, v116
	s_waitcnt lgkmcnt(0)
	ds_read_b128 v[34:37], v3 offset:3584
	ds_read_b128 v[38:41], v3 offset:3600
	ds_read_b128 v[42:45], v3 offset:3616
	ds_read_b128 v[46:49], v3 offset:3632
	ds_read_b128 v[200:203], v3 offset:3648
	ds_read_b128 v[204:207], v3 offset:3664
	ds_read_b128 v[208:211], v3 offset:3680
	ds_read_b128 v[212:215], v3 offset:3696
	v_fma_f32 v50, v16, v216, v32
	v_fma_f32 v51, v16, v236, v32
	v_fmac_f32_e32 v50, v17, v217
	v_fmac_f32_e32 v51, v17, v237
	v_fmac_f32_e32 v50, v18, v218
	v_fmac_f32_e32 v51, v18, v238
	v_fmac_f32_e32 v50, v19, v219
	v_fmac_f32_e32 v51, v19, v239
	v_fmac_f32_e32 v50, v20, v220
	v_fmac_f32_e32 v51, v20, v240
	v_fmac_f32_e32 v50, v21, v221
	v_fmac_f32_e32 v51, v21, v241
	v_fmac_f32_e32 v50, v22, v222
	v_fmac_f32_e32 v51, v22, v242
	v_fmac_f32_e32 v50, v23, v223
	v_fmac_f32_e32 v51, v23, v243
	v_fmac_f32_e32 v50, v24, v224
	v_fmac_f32_e32 v51, v24, v244
	v_fmac_f32_e32 v50, v25, v225
	v_fmac_f32_e32 v51, v25, v245
	v_fmac_f32_e32 v50, v26, v226
	v_fmac_f32_e32 v51, v26, v246
	v_fmac_f32_e32 v50, v27, v227
	v_fmac_f32_e32 v51, v27, v247
	v_fmac_f32_e32 v50, v28, v232
	v_fmac_f32_e32 v51, v28, v248
	v_fmac_f32_e32 v50, v29, v233
	v_fmac_f32_e32 v51, v29, v249
	v_fmac_f32_e32 v50, v30, v234
	v_fmac_f32_e32 v51, v30, v250
	v_fmac_f32_e32 v50, v31, v235
	v_fmac_f32_e32 v51, v31, v251
	v_mul_f32_e64 v52, |v50|, s7
	v_mul_f32_e64 v53, |v51|, s7
	v_exp_f32_e32 v52, v52
	v_exp_f32_e32 v53, v53
	v_min_f32_e32 v50, 0, v50
	v_add_f32_e32 v52, 1.0, v52
	v_add_f32_e32 v53, 1.0, v53
	v_log_f32_e32 v52, v52
	v_log_f32_e32 v53, v53
	v_min_f32_e32 v51, 0, v51
	v_mul_f32_e32 v54, 0x3f317217, v52
	v_mul_f32_e32 v55, 0x3f317217, v53
	v_fma_f32 v56, v52, s9, -v54
	v_fma_f32 v57, v53, s9, -v55
	v_fmac_f32_e32 v56, 0x3377d1cf, v52
	v_fmac_f32_e32 v57, 0x3377d1cf, v53
	v_add_f32_e32 v54, v54, v56
	v_add_f32_e32 v55, v55, v57
	v_sub_f32_e32 v50, v50, v54
	v_sub_f32_e32 v51, v51, v55
	v_fmamk_f32 v118, v50, 0x3d800000, v117
	v_fmamk_f32 v119, v51, 0x3d800000, v118
	s_waitcnt lgkmcnt(0)
	ds_read_b128 v[216:219], v3 offset:3712
	ds_read_b128 v[220:223], v3 offset:3728
	ds_read_b128 v[224:227], v3 offset:3744
	ds_read_b128 v[232:235], v3 offset:3760
	ds_read_b128 v[236:239], v3 offset:3776
	ds_read_b128 v[240:243], v3 offset:3792
	ds_read_b128 v[244:247], v3 offset:3808
	ds_read_b128 v[248:251], v3 offset:3824
	v_fma_f32 v50, v16, v34, v32
	v_fma_f32 v51, v16, v200, v32
	v_fmac_f32_e32 v50, v17, v35
	v_fmac_f32_e32 v51, v17, v201
	v_fmac_f32_e32 v50, v18, v36
	v_fmac_f32_e32 v51, v18, v202
	v_fmac_f32_e32 v50, v19, v37
	v_fmac_f32_e32 v51, v19, v203
	v_fmac_f32_e32 v50, v20, v38
	v_fmac_f32_e32 v51, v20, v204
	v_fmac_f32_e32 v50, v21, v39
	v_fmac_f32_e32 v51, v21, v205
	v_fmac_f32_e32 v50, v22, v40
	v_fmac_f32_e32 v51, v22, v206
	v_fmac_f32_e32 v50, v23, v41
	v_fmac_f32_e32 v51, v23, v207
	v_fmac_f32_e32 v50, v24, v42
	v_fmac_f32_e32 v51, v24, v208
	v_fmac_f32_e32 v50, v25, v43
	v_fmac_f32_e32 v51, v25, v209
	v_fmac_f32_e32 v50, v26, v44
	v_fmac_f32_e32 v51, v26, v210
	v_fmac_f32_e32 v50, v27, v45
	v_fmac_f32_e32 v51, v27, v211
	v_fmac_f32_e32 v50, v28, v46
	v_fmac_f32_e32 v51, v28, v212
	v_fmac_f32_e32 v50, v29, v47
	v_fmac_f32_e32 v51, v29, v213
	v_fmac_f32_e32 v50, v30, v48
	v_fmac_f32_e32 v51, v30, v214
	v_fmac_f32_e32 v50, v31, v49
	v_fmac_f32_e32 v51, v31, v215
	v_mul_f32_e64 v52, |v50|, s7
	v_mul_f32_e64 v53, |v51|, s7
	v_exp_f32_e32 v52, v52
	v_exp_f32_e32 v53, v53
	v_min_f32_e32 v50, 0, v50
	v_add_f32_e32 v52, 1.0, v52
	v_add_f32_e32 v53, 1.0, v53
	v_log_f32_e32 v52, v52
	v_log_f32_e32 v53, v53
	v_min_f32_e32 v51, 0, v51
	v_mul_f32_e32 v54, 0x3f317217, v52
	v_mul_f32_e32 v55, 0x3f317217, v53
	v_fma_f32 v56, v52, s9, -v54
	v_fma_f32 v57, v53, s9, -v55
	v_fmac_f32_e32 v56, 0x3377d1cf, v52
	v_fmac_f32_e32 v57, 0x3377d1cf, v53
	v_add_f32_e32 v54, v54, v56
	v_add_f32_e32 v55, v55, v57
	v_sub_f32_e32 v50, v50, v54
	v_sub_f32_e32 v51, v51, v55
	v_fmamk_f32 v120, v50, 0x3d800000, v119
	v_fmamk_f32 v121, v51, 0x3d800000, v120
	s_waitcnt lgkmcnt(0)
	ds_read_b128 v[34:37], v3 offset:3840
	ds_read_b128 v[38:41], v3 offset:3856
	ds_read_b128 v[42:45], v3 offset:3872
	ds_read_b128 v[46:49], v3 offset:3888
	ds_read_b128 v[200:203], v3 offset:3904
	ds_read_b128 v[204:207], v3 offset:3920
	ds_read_b128 v[208:211], v3 offset:3936
	ds_read_b128 v[212:215], v3 offset:3952
	v_fma_f32 v50, v16, v216, v32
	v_fma_f32 v51, v16, v236, v32
	v_fmac_f32_e32 v50, v17, v217
	v_fmac_f32_e32 v51, v17, v237
	v_fmac_f32_e32 v50, v18, v218
	v_fmac_f32_e32 v51, v18, v238
	v_fmac_f32_e32 v50, v19, v219
	v_fmac_f32_e32 v51, v19, v239
	v_fmac_f32_e32 v50, v20, v220
	v_fmac_f32_e32 v51, v20, v240
	v_fmac_f32_e32 v50, v21, v221
	v_fmac_f32_e32 v51, v21, v241
	v_fmac_f32_e32 v50, v22, v222
	v_fmac_f32_e32 v51, v22, v242
	v_fmac_f32_e32 v50, v23, v223
	v_fmac_f32_e32 v51, v23, v243
	v_fmac_f32_e32 v50, v24, v224
	v_fmac_f32_e32 v51, v24, v244
	v_fmac_f32_e32 v50, v25, v225
	v_fmac_f32_e32 v51, v25, v245
	v_fmac_f32_e32 v50, v26, v226
	v_fmac_f32_e32 v51, v26, v246
	v_fmac_f32_e32 v50, v27, v227
	v_fmac_f32_e32 v51, v27, v247
	v_fmac_f32_e32 v50, v28, v232
	v_fmac_f32_e32 v51, v28, v248
	v_fmac_f32_e32 v50, v29, v233
	v_fmac_f32_e32 v51, v29, v249
	v_fmac_f32_e32 v50, v30, v234
	v_fmac_f32_e32 v51, v30, v250
	v_fmac_f32_e32 v50, v31, v235
	v_fmac_f32_e32 v51, v31, v251
	v_mul_f32_e64 v52, |v50|, s7
	v_mul_f32_e64 v53, |v51|, s7
	v_exp_f32_e32 v52, v52
	v_exp_f32_e32 v53, v53
	v_min_f32_e32 v50, 0, v50
	v_add_f32_e32 v52, 1.0, v52
	v_add_f32_e32 v53, 1.0, v53
	v_log_f32_e32 v52, v52
	v_log_f32_e32 v53, v53
	v_min_f32_e32 v51, 0, v51
	v_mul_f32_e32 v54, 0x3f317217, v52
	v_mul_f32_e32 v55, 0x3f317217, v53
	v_fma_f32 v56, v52, s9, -v54
	v_fma_f32 v57, v53, s9, -v55
	v_fmac_f32_e32 v56, 0x3377d1cf, v52
	v_fmac_f32_e32 v57, 0x3377d1cf, v53
	v_add_f32_e32 v54, v54, v56
	v_add_f32_e32 v55, v55, v57
	v_sub_f32_e32 v50, v50, v54
	v_sub_f32_e32 v51, v51, v55
	v_fmamk_f32 v122, v50, 0x3d800000, v121
	v_fmamk_f32 v123, v51, 0x3d800000, v122
	s_waitcnt lgkmcnt(0)
	ds_read_b128 v[216:219], v3 offset:3968
	ds_read_b128 v[220:223], v3 offset:3984
	ds_read_b128 v[224:227], v3 offset:4000
	ds_read_b128 v[232:235], v3 offset:4016
	ds_read_b128 v[236:239], v3 offset:4032
	ds_read_b128 v[240:243], v3 offset:4048
	ds_read_b128 v[244:247], v3 offset:4064
	ds_read_b128 v[248:251], v3 offset:4080
	v_fma_f32 v50, v16, v34, v32
	v_fma_f32 v51, v16, v200, v32
	v_fmac_f32_e32 v50, v17, v35
	v_fmac_f32_e32 v51, v17, v201
	v_fmac_f32_e32 v50, v18, v36
	v_fmac_f32_e32 v51, v18, v202
	v_fmac_f32_e32 v50, v19, v37
	v_fmac_f32_e32 v51, v19, v203
	v_fmac_f32_e32 v50, v20, v38
	v_fmac_f32_e32 v51, v20, v204
	v_fmac_f32_e32 v50, v21, v39
	v_fmac_f32_e32 v51, v21, v205
	v_fmac_f32_e32 v50, v22, v40
	v_fmac_f32_e32 v51, v22, v206
	v_fmac_f32_e32 v50, v23, v41
	v_fmac_f32_e32 v51, v23, v207
	v_fmac_f32_e32 v50, v24, v42
	v_fmac_f32_e32 v51, v24, v208
	v_fmac_f32_e32 v50, v25, v43
	v_fmac_f32_e32 v51, v25, v209
	v_fmac_f32_e32 v50, v26, v44
	v_fmac_f32_e32 v51, v26, v210
	v_fmac_f32_e32 v50, v27, v45
	v_fmac_f32_e32 v51, v27, v211
	v_fmac_f32_e32 v50, v28, v46
	v_fmac_f32_e32 v51, v28, v212
	v_fmac_f32_e32 v50, v29, v47
	v_fmac_f32_e32 v51, v29, v213
	v_fmac_f32_e32 v50, v30, v48
	v_fmac_f32_e32 v51, v30, v214
	v_fmac_f32_e32 v50, v31, v49
	v_fmac_f32_e32 v51, v31, v215
	v_mul_f32_e64 v52, |v50|, s7
	v_mul_f32_e64 v53, |v51|, s7
	v_exp_f32_e32 v52, v52
	v_exp_f32_e32 v53, v53
	v_min_f32_e32 v50, 0, v50
	v_add_f32_e32 v52, 1.0, v52
	v_add_f32_e32 v53, 1.0, v53
	v_log_f32_e32 v52, v52
	v_log_f32_e32 v53, v53
	v_min_f32_e32 v51, 0, v51
	v_mul_f32_e32 v54, 0x3f317217, v52
	v_mul_f32_e32 v55, 0x3f317217, v53
	v_fma_f32 v56, v52, s9, -v54
	v_fma_f32 v57, v53, s9, -v55
	v_fmac_f32_e32 v56, 0x3377d1cf, v52
	v_fmac_f32_e32 v57, 0x3377d1cf, v53
	v_add_f32_e32 v54, v54, v56
	v_add_f32_e32 v55, v55, v57
	v_sub_f32_e32 v50, v50, v54
	v_sub_f32_e32 v51, v51, v55
	v_fmamk_f32 v124, v50, 0x3d800000, v123
	v_fmamk_f32 v125, v51, 0x3d800000, v124
	s_waitcnt lgkmcnt(0)
	v_fma_f32 v50, v16, v216, v32
	v_fma_f32 v51, v16, v236, v32
	v_fmac_f32_e32 v50, v17, v217
	v_fmac_f32_e32 v51, v17, v237
	v_fmac_f32_e32 v50, v18, v218
	v_fmac_f32_e32 v51, v18, v238
	v_fmac_f32_e32 v50, v19, v219
	v_fmac_f32_e32 v51, v19, v239
	v_fmac_f32_e32 v50, v20, v220
	v_fmac_f32_e32 v51, v20, v240
	v_fmac_f32_e32 v50, v21, v221
	v_fmac_f32_e32 v51, v21, v241
	v_fmac_f32_e32 v50, v22, v222
	v_fmac_f32_e32 v51, v22, v242
	v_fmac_f32_e32 v50, v23, v223
	v_fmac_f32_e32 v51, v23, v243
	v_fmac_f32_e32 v50, v24, v224
	v_fmac_f32_e32 v51, v24, v244
	v_fmac_f32_e32 v50, v25, v225
	v_fmac_f32_e32 v51, v25, v245
	v_fmac_f32_e32 v50, v26, v226
	v_fmac_f32_e32 v51, v26, v246
	v_fmac_f32_e32 v50, v27, v227
	v_fmac_f32_e32 v51, v27, v247
	v_fmac_f32_e32 v50, v28, v232
	v_fmac_f32_e32 v51, v28, v248
	v_fmac_f32_e32 v50, v29, v233
	v_fmac_f32_e32 v51, v29, v249
	v_fmac_f32_e32 v50, v30, v234
	v_fmac_f32_e32 v51, v30, v250
	v_fmac_f32_e32 v50, v31, v235
	v_fmac_f32_e32 v51, v31, v251
	v_mul_f32_e64 v52, |v50|, s7
	v_mul_f32_e64 v53, |v51|, s7
	v_exp_f32_e32 v52, v52
	v_exp_f32_e32 v53, v53
	v_min_f32_e32 v50, 0, v50
	v_add_f32_e32 v52, 1.0, v52
	v_add_f32_e32 v53, 1.0, v53
	v_log_f32_e32 v52, v52
	v_log_f32_e32 v53, v53
	v_min_f32_e32 v51, 0, v51
	v_mul_f32_e32 v54, 0x3f317217, v52
	v_mul_f32_e32 v55, 0x3f317217, v53
	v_fma_f32 v56, v52, s9, -v54
	v_fma_f32 v57, v53, s9, -v55
	v_fmac_f32_e32 v56, 0x3377d1cf, v52
	v_fmac_f32_e32 v57, 0x3377d1cf, v53
	v_add_f32_e32 v54, v54, v56
	v_add_f32_e32 v55, v55, v57
	v_sub_f32_e32 v50, v50, v54
	v_sub_f32_e32 v51, v51, v55
	v_fmamk_f32 v126, v50, 0x3d800000, v125
	v_fmamk_f32 v127, v51, 0x3d800000, v126
	s_waitcnt vmcnt(0)
	v_sub_f32_e32 v52, v96, v96
	v_lshlrev_b32_e32 v50, 16, v136
	v_mul_f32_e32 v52, 0x3fb8aa3b, v52
	v_lshlrev_b32_e32 v51, 16, v137
	v_exp_f32_e32 v53, v52
	v_exp_f32_e64 v54, -v52
	v_mul_f32_e32 v50, 0x3db504f3, v50
	s_nop 0
	v_mul_f32_e32 v50, v53, v50
	v_mul_f32_e32 v8, v54, v51
	v_cvt_pk_bf16_f32 v50, v50, v8
	global_store_short v1, v50, s[22:23]
	global_store_short_d16_hi v1, v50, s[22:23] offset:1024
	s_add_u32 s22, s22, 0x1a00
	s_addc_u32 s23, s23, 0
	v_sub_f32_e32 v52, v97, v96
	v_lshlrev_b32_e32 v50, 16, v138
	v_mul_f32_e32 v52, 0x3fb8aa3b, v52
	v_lshlrev_b32_e32 v51, 16, v139
	v_exp_f32_e32 v53, v52
	v_exp_f32_e64 v54, -v52
	v_mul_f32_e32 v50, 0x3db504f3, v50
	s_nop 0
	v_mul_f32_e32 v50, v53, v50
	v_mul_f32_e32 v9, v54, v51
	v_cvt_pk_bf16_f32 v50, v50, v9
	global_store_short v1, v50, s[22:23]
	global_store_short_d16_hi v1, v50, s[22:23] offset:1024
	s_add_u32 s22, s22, 0x1a00
	s_addc_u32 s23, s23, 0
	v_sub_f32_e32 v52, v98, v96
	v_lshlrev_b32_e32 v50, 16, v140
	v_mul_f32_e32 v52, 0x3fb8aa3b, v52
	v_lshlrev_b32_e32 v51, 16, v141
	v_exp_f32_e32 v53, v52
	v_exp_f32_e64 v54, -v52
	v_mul_f32_e32 v50, 0x3db504f3, v50
	s_nop 0
	v_mul_f32_e32 v50, v53, v50
	v_mul_f32_e32 v10, v54, v51
	v_cvt_pk_bf16_f32 v50, v50, v10
	global_store_short v1, v50, s[22:23]
	global_store_short_d16_hi v1, v50, s[22:23] offset:1024
	s_add_u32 s22, s22, 0x1a00
	s_addc_u32 s23, s23, 0
	v_sub_f32_e32 v52, v99, v96
	v_lshlrev_b32_e32 v50, 16, v142
	v_mul_f32_e32 v52, 0x3fb8aa3b, v52
	v_lshlrev_b32_e32 v51, 16, v143
	v_exp_f32_e32 v53, v52
	v_exp_f32_e64 v54, -v52
	v_mul_f32_e32 v50, 0x3db504f3, v50
	s_nop 0
	v_mul_f32_e32 v50, v53, v50
	v_mul_f32_e32 v11, v54, v51
	v_cvt_pk_bf16_f32 v50, v50, v11
	global_store_short v1, v50, s[22:23]
	global_store_short_d16_hi v1, v50, s[22:23] offset:1024
	s_add_u32 s22, s22, 0x1a00
	s_addc_u32 s23, s23, 0
	v_sub_f32_e32 v52, v100, v96
	v_lshlrev_b32_e32 v50, 16, v144
	v_mul_f32_e32 v52, 0x3fb8aa3b, v52
	v_lshlrev_b32_e32 v51, 16, v145
	v_exp_f32_e32 v53, v52
	v_exp_f32_e64 v54, -v52
	v_mul_f32_e32 v50, 0x3db504f3, v50
	s_nop 0
	v_mul_f32_e32 v50, v53, v50
	v_mul_f32_e32 v12, v54, v51
	v_cvt_pk_bf16_f32 v50, v50, v12
	global_store_short v1, v50, s[22:23]
	global_store_short_d16_hi v1, v50, s[22:23] offset:1024
	s_add_u32 s22, s22, 0x1a00
	s_addc_u32 s23, s23, 0
	v_sub_f32_e32 v52, v101, v96
	v_lshlrev_b32_e32 v50, 16, v146
	v_mul_f32_e32 v52, 0x3fb8aa3b, v52
	v_lshlrev_b32_e32 v51, 16, v147
	v_exp_f32_e32 v53, v52
	v_exp_f32_e64 v54, -v52
	v_mul_f32_e32 v50, 0x3db504f3, v50
	s_nop 0
	v_mul_f32_e32 v50, v53, v50
	v_mul_f32_e32 v13, v54, v51
	v_cvt_pk_bf16_f32 v50, v50, v13
	global_store_short v1, v50, s[22:23]
	global_store_short_d16_hi v1, v50, s[22:23] offset:1024
	s_add_u32 s22, s22, 0x1a00
	s_addc_u32 s23, s23, 0
	v_sub_f32_e32 v52, v102, v96
	v_lshlrev_b32_e32 v50, 16, v148
	v_mul_f32_e32 v52, 0x3fb8aa3b, v52
	v_lshlrev_b32_e32 v51, 16, v149
	v_exp_f32_e32 v53, v52
	v_exp_f32_e64 v54, -v52
	v_mul_f32_e32 v50, 0x3db504f3, v50
	s_nop 0
	v_mul_f32_e32 v50, v53, v50
	v_mul_f32_e32 v14, v54, v51
	v_cvt_pk_bf16_f32 v50, v50, v14
	global_store_short v1, v50, s[22:23]
	global_store_short_d16_hi v1, v50, s[22:23] offset:1024
	s_add_u32 s22, s22, 0x1a00
	s_addc_u32 s23, s23, 0
	v_sub_f32_e32 v52, v103, v96
	v_lshlrev_b32_e32 v50, 16, v150
	v_mul_f32_e32 v52, 0x3fb8aa3b, v52
	v_lshlrev_b32_e32 v51, 16, v151
	v_exp_f32_e32 v53, v52
	v_exp_f32_e64 v54, -v52
	v_mul_f32_e32 v50, 0x3db504f3, v50
	s_nop 0
	v_mul_f32_e32 v50, v53, v50
	v_mul_f32_e32 v15, v54, v51
	v_cvt_pk_bf16_f32 v50, v50, v15
	global_store_short v1, v50, s[22:23]
	global_store_short_d16_hi v1, v50, s[22:23] offset:1024
	s_add_u32 s22, s22, 0x1a00
	s_addc_u32 s23, s23, 0
	v_cvt_pk_bf16_f32 v4, v8, v9
	v_cvt_pk_bf16_f32 v5, v10, v11
	v_cvt_pk_bf16_f32 v6, v12, v13
	v_cvt_pk_bf16_f32 v7, v14, v15
	global_store_dwordx4 v2, v[4:7], s[26:27] offset:64
	v_sub_f32_e32 v52, v104, v96
	v_lshlrev_b32_e32 v50, 16, v152
	v_mul_f32_e32 v52, 0x3fb8aa3b, v52
	v_lshlrev_b32_e32 v51, 16, v153
	v_exp_f32_e32 v53, v52
	v_exp_f32_e64 v54, -v52
	v_mul_f32_e32 v50, 0x3db504f3, v50
	s_nop 0
	v_mul_f32_e32 v50, v53, v50
	v_mul_f32_e32 v8, v54, v51
	v_cvt_pk_bf16_f32 v50, v50, v8
	global_store_short v1, v50, s[22:23]
	global_store_short_d16_hi v1, v50, s[22:23] offset:1024
	s_add_u32 s22, s22, 0x1a00
	s_addc_u32 s23, s23, 0
	v_sub_f32_e32 v52, v105, v96
	v_lshlrev_b32_e32 v50, 16, v154
	v_mul_f32_e32 v52, 0x3fb8aa3b, v52
	v_lshlrev_b32_e32 v51, 16, v155
	v_exp_f32_e32 v53, v52
	v_exp_f32_e64 v54, -v52
	v_mul_f32_e32 v50, 0x3db504f3, v50
	s_nop 0
	v_mul_f32_e32 v50, v53, v50
	v_mul_f32_e32 v9, v54, v51
	v_cvt_pk_bf16_f32 v50, v50, v9
	global_store_short v1, v50, s[22:23]
	global_store_short_d16_hi v1, v50, s[22:23] offset:1024
	s_add_u32 s22, s22, 0x1a00
	s_addc_u32 s23, s23, 0
	v_sub_f32_e32 v52, v106, v96
	v_lshlrev_b32_e32 v50, 16, v156
	v_mul_f32_e32 v52, 0x3fb8aa3b, v52
	v_lshlrev_b32_e32 v51, 16, v157
	v_exp_f32_e32 v53, v52
	v_exp_f32_e64 v54, -v52
	v_mul_f32_e32 v50, 0x3db504f3, v50
	s_nop 0
	v_mul_f32_e32 v50, v53, v50
	v_mul_f32_e32 v10, v54, v51
	v_cvt_pk_bf16_f32 v50, v50, v10
	global_store_short v1, v50, s[22:23]
	global_store_short_d16_hi v1, v50, s[22:23] offset:1024
	s_add_u32 s22, s22, 0x1a00
	s_addc_u32 s23, s23, 0
	v_sub_f32_e32 v52, v107, v96
	v_lshlrev_b32_e32 v50, 16, v158
	v_mul_f32_e32 v52, 0x3fb8aa3b, v52
	v_lshlrev_b32_e32 v51, 16, v159
	v_exp_f32_e32 v53, v52
	v_exp_f32_e64 v54, -v52
	v_mul_f32_e32 v50, 0x3db504f3, v50
	s_nop 0
	v_mul_f32_e32 v50, v53, v50
	v_mul_f32_e32 v11, v54, v51
	v_cvt_pk_bf16_f32 v50, v50, v11
	global_store_short v1, v50, s[22:23]
	global_store_short_d16_hi v1, v50, s[22:23] offset:1024
	s_add_u32 s22, s22, 0x1a00
	s_addc_u32 s23, s23, 0
	v_sub_f32_e32 v52, v108, v96
	v_lshlrev_b32_e32 v50, 16, v160
	v_mul_f32_e32 v52, 0x3fb8aa3b, v52
	v_lshlrev_b32_e32 v51, 16, v161
	v_exp_f32_e32 v53, v52
	v_exp_f32_e64 v54, -v52
	v_mul_f32_e32 v50, 0x3db504f3, v50
	s_nop 0
	v_mul_f32_e32 v50, v53, v50
	v_mul_f32_e32 v12, v54, v51
	v_cvt_pk_bf16_f32 v50, v50, v12
	global_store_short v1, v50, s[22:23]
	global_store_short_d16_hi v1, v50, s[22:23] offset:1024
	s_add_u32 s22, s22, 0x1a00
	s_addc_u32 s23, s23, 0
	v_sub_f32_e32 v52, v109, v96
	v_lshlrev_b32_e32 v50, 16, v162
	v_mul_f32_e32 v52, 0x3fb8aa3b, v52
	v_lshlrev_b32_e32 v51, 16, v163
	v_exp_f32_e32 v53, v52
	v_exp_f32_e64 v54, -v52
	v_mul_f32_e32 v50, 0x3db504f3, v50
	s_nop 0
	v_mul_f32_e32 v50, v53, v50
	v_mul_f32_e32 v13, v54, v51
	v_cvt_pk_bf16_f32 v50, v50, v13
	global_store_short v1, v50, s[22:23]
	global_store_short_d16_hi v1, v50, s[22:23] offset:1024
	s_add_u32 s22, s22, 0x1a00
	s_addc_u32 s23, s23, 0
	v_sub_f32_e32 v52, v110, v96
	v_lshlrev_b32_e32 v50, 16, v164
	v_mul_f32_e32 v52, 0x3fb8aa3b, v52
	v_lshlrev_b32_e32 v51, 16, v165
	v_exp_f32_e32 v53, v52
	v_exp_f32_e64 v54, -v52
	v_mul_f32_e32 v50, 0x3db504f3, v50
	s_nop 0
	v_mul_f32_e32 v50, v53, v50
	v_mul_f32_e32 v14, v54, v51
	v_cvt_pk_bf16_f32 v50, v50, v14
	global_store_short v1, v50, s[22:23]
	global_store_short_d16_hi v1, v50, s[22:23] offset:1024
	s_add_u32 s22, s22, 0x1a00
	s_addc_u32 s23, s23, 0
	v_sub_f32_e32 v52, v111, v96
	v_lshlrev_b32_e32 v50, 16, v166
	v_mul_f32_e32 v52, 0x3fb8aa3b, v52
	v_lshlrev_b32_e32 v51, 16, v167
	v_exp_f32_e32 v53, v52
	v_exp_f32_e64 v54, -v52
	v_mul_f32_e32 v50, 0x3db504f3, v50
	s_nop 0
	v_mul_f32_e32 v50, v53, v50
	v_mul_f32_e32 v15, v54, v51
	v_cvt_pk_bf16_f32 v50, v50, v15
	global_store_short v1, v50, s[22:23]
	global_store_short_d16_hi v1, v50, s[22:23] offset:1024
	s_add_u32 s22, s22, 0x1a00
	s_addc_u32 s23, s23, 0
	v_cvt_pk_bf16_f32 v4, v8, v9
	v_cvt_pk_bf16_f32 v5, v10, v11
	v_cvt_pk_bf16_f32 v6, v12, v13
	v_cvt_pk_bf16_f32 v7, v14, v15
	global_store_dwordx4 v2, v[4:7], s[26:27] offset:80
	v_sub_f32_e32 v52, v112, v96
	v_lshlrev_b32_e32 v50, 16, v168
	v_mul_f32_e32 v52, 0x3fb8aa3b, v52
	v_lshlrev_b32_e32 v51, 16, v169
	v_exp_f32_e32 v53, v52
	v_exp_f32_e64 v54, -v52
	v_mul_f32_e32 v50, 0x3db504f3, v50
	s_nop 0
	v_mul_f32_e32 v50, v53, v50
	v_mul_f32_e32 v8, v54, v51
	v_cvt_pk_bf16_f32 v50, v50, v8
	global_store_short v1, v50, s[22:23]
	global_store_short_d16_hi v1, v50, s[22:23] offset:1024
	s_add_u32 s22, s22, 0x1a00
	s_addc_u32 s23, s23, 0
	v_sub_f32_e32 v52, v113, v96
	v_lshlrev_b32_e32 v50, 16, v170
	v_mul_f32_e32 v52, 0x3fb8aa3b, v52
	v_lshlrev_b32_e32 v51, 16, v171
	v_exp_f32_e32 v53, v52
	v_exp_f32_e64 v54, -v52
	v_mul_f32_e32 v50, 0x3db504f3, v50
	s_nop 0
	v_mul_f32_e32 v50, v53, v50
	v_mul_f32_e32 v9, v54, v51
	v_cvt_pk_bf16_f32 v50, v50, v9
	global_store_short v1, v50, s[22:23]
	global_store_short_d16_hi v1, v50, s[22:23] offset:1024
	s_add_u32 s22, s22, 0x1a00
	s_addc_u32 s23, s23, 0
	v_sub_f32_e32 v52, v114, v96
	v_lshlrev_b32_e32 v50, 16, v172
	v_mul_f32_e32 v52, 0x3fb8aa3b, v52
	v_lshlrev_b32_e32 v51, 16, v173
	v_exp_f32_e32 v53, v52
	v_exp_f32_e64 v54, -v52
	v_mul_f32_e32 v50, 0x3db504f3, v50
	s_nop 0
	v_mul_f32_e32 v50, v53, v50
	v_mul_f32_e32 v10, v54, v51
	v_cvt_pk_bf16_f32 v50, v50, v10
	global_store_short v1, v50, s[22:23]
	global_store_short_d16_hi v1, v50, s[22:23] offset:1024
	s_add_u32 s22, s22, 0x1a00
	s_addc_u32 s23, s23, 0
	v_sub_f32_e32 v52, v115, v96
	v_lshlrev_b32_e32 v50, 16, v174
	v_mul_f32_e32 v52, 0x3fb8aa3b, v52
	v_lshlrev_b32_e32 v51, 16, v175
	v_exp_f32_e32 v53, v52
	v_exp_f32_e64 v54, -v52
	v_mul_f32_e32 v50, 0x3db504f3, v50
	s_nop 0
	v_mul_f32_e32 v50, v53, v50
	v_mul_f32_e32 v11, v54, v51
	v_cvt_pk_bf16_f32 v50, v50, v11
	global_store_short v1, v50, s[22:23]
	global_store_short_d16_hi v1, v50, s[22:23] offset:1024
	s_add_u32 s22, s22, 0x1a00
	s_addc_u32 s23, s23, 0
	v_sub_f32_e32 v52, v116, v96
	v_lshlrev_b32_e32 v50, 16, v176
	v_mul_f32_e32 v52, 0x3fb8aa3b, v52
	v_lshlrev_b32_e32 v51, 16, v177
	v_exp_f32_e32 v53, v52
	v_exp_f32_e64 v54, -v52
	v_mul_f32_e32 v50, 0x3db504f3, v50
	s_nop 0
	v_mul_f32_e32 v50, v53, v50
	v_mul_f32_e32 v12, v54, v51
	v_cvt_pk_bf16_f32 v50, v50, v12
	global_store_short v1, v50, s[22:23]
	global_store_short_d16_hi v1, v50, s[22:23] offset:1024
	s_add_u32 s22, s22, 0x1a00
	s_addc_u32 s23, s23, 0
	v_sub_f32_e32 v52, v117, v96
	v_lshlrev_b32_e32 v50, 16, v178
	v_mul_f32_e32 v52, 0x3fb8aa3b, v52
	v_lshlrev_b32_e32 v51, 16, v179
	v_exp_f32_e32 v53, v52
	v_exp_f32_e64 v54, -v52
	v_mul_f32_e32 v50, 0x3db504f3, v50
	s_nop 0
	v_mul_f32_e32 v50, v53, v50
	v_mul_f32_e32 v13, v54, v51
	v_cvt_pk_bf16_f32 v50, v50, v13
	global_store_short v1, v50, s[22:23]
	global_store_short_d16_hi v1, v50, s[22:23] offset:1024
	s_add_u32 s22, s22, 0x1a00
	s_addc_u32 s23, s23, 0
	v_sub_f32_e32 v52, v118, v96
	v_lshlrev_b32_e32 v50, 16, v180
	v_mul_f32_e32 v52, 0x3fb8aa3b, v52
	v_lshlrev_b32_e32 v51, 16, v181
	v_exp_f32_e32 v53, v52
	v_exp_f32_e64 v54, -v52
	v_mul_f32_e32 v50, 0x3db504f3, v50
	s_nop 0
	v_mul_f32_e32 v50, v53, v50
	v_mul_f32_e32 v14, v54, v51
	v_cvt_pk_bf16_f32 v50, v50, v14
	global_store_short v1, v50, s[22:23]
	global_store_short_d16_hi v1, v50, s[22:23] offset:1024
	s_add_u32 s22, s22, 0x1a00
	s_addc_u32 s23, s23, 0
	v_sub_f32_e32 v52, v119, v96
	v_lshlrev_b32_e32 v50, 16, v182
	v_mul_f32_e32 v52, 0x3fb8aa3b, v52
	v_lshlrev_b32_e32 v51, 16, v183
	v_exp_f32_e32 v53, v52
	v_exp_f32_e64 v54, -v52
	v_mul_f32_e32 v50, 0x3db504f3, v50
	s_nop 0
	v_mul_f32_e32 v50, v53, v50
	v_mul_f32_e32 v15, v54, v51
	v_cvt_pk_bf16_f32 v50, v50, v15
	global_store_short v1, v50, s[22:23]
	global_store_short_d16_hi v1, v50, s[22:23] offset:1024
	s_add_u32 s22, s22, 0x1a00
	s_addc_u32 s23, s23, 0
	v_cvt_pk_bf16_f32 v4, v8, v9
	v_cvt_pk_bf16_f32 v5, v10, v11
	v_cvt_pk_bf16_f32 v6, v12, v13
	v_cvt_pk_bf16_f32 v7, v14, v15
	global_store_dwordx4 v2, v[4:7], s[26:27] offset:96
	s_waitcnt vmcnt(52)
	v_sub_f32_e32 v52, v120, v96
	v_lshlrev_b32_e32 v50, 16, v184
	v_mul_f32_e32 v52, 0x3fb8aa3b, v52
	v_lshlrev_b32_e32 v51, 16, v185
	v_exp_f32_e32 v53, v52
	v_exp_f32_e64 v54, -v52
	v_mul_f32_e32 v50, 0x3db504f3, v50
	s_nop 0
	v_mul_f32_e32 v50, v53, v50
	v_mul_f32_e32 v8, v54, v51
	v_cvt_pk_bf16_f32 v50, v50, v8
	global_store_short v1, v50, s[22:23]
	global_store_short_d16_hi v1, v50, s[22:23] offset:1024
	s_add_u32 s22, s22, 0x1a00
	s_addc_u32 s23, s23, 0
	s_waitcnt vmcnt(52)
	v_sub_f32_e32 v52, v121, v96
	v_lshlrev_b32_e32 v50, 16, v186
	v_mul_f32_e32 v52, 0x3fb8aa3b, v52
	v_lshlrev_b32_e32 v51, 16, v187
	v_exp_f32_e32 v53, v52
	v_exp_f32_e64 v54, -v52
	v_mul_f32_e32 v50, 0x3db504f3, v50
	s_nop 0
	v_mul_f32_e32 v50, v53, v50
	v_mul_f32_e32 v9, v54, v51
	v_cvt_pk_bf16_f32 v50, v50, v9
	global_store_short v1, v50, s[22:23]
	global_store_short_d16_hi v1, v50, s[22:23] offset:1024
	s_add_u32 s22, s22, 0x1a00
	s_addc_u32 s23, s23, 0
	s_waitcnt vmcnt(52)
	v_sub_f32_e32 v52, v122, v96
	v_lshlrev_b32_e32 v50, 16, v188
	v_mul_f32_e32 v52, 0x3fb8aa3b, v52
	v_lshlrev_b32_e32 v51, 16, v189
	v_exp_f32_e32 v53, v52
	v_exp_f32_e64 v54, -v52
	v_mul_f32_e32 v50, 0x3db504f3, v50
	s_nop 0
	v_mul_f32_e32 v50, v53, v50
	v_mul_f32_e32 v10, v54, v51
	v_cvt_pk_bf16_f32 v50, v50, v10
	global_store_short v1, v50, s[22:23]
	global_store_short_d16_hi v1, v50, s[22:23] offset:1024
	s_add_u32 s22, s22, 0x1a00
	s_addc_u32 s23, s23, 0
	s_waitcnt vmcnt(52)
	v_sub_f32_e32 v52, v123, v96
	v_lshlrev_b32_e32 v50, 16, v190
	v_mul_f32_e32 v52, 0x3fb8aa3b, v52
	v_lshlrev_b32_e32 v51, 16, v191
	v_exp_f32_e32 v53, v52
	v_exp_f32_e64 v54, -v52
	v_mul_f32_e32 v50, 0x3db504f3, v50
	s_nop 0
	v_mul_f32_e32 v50, v53, v50
	v_mul_f32_e32 v11, v54, v51
	v_cvt_pk_bf16_f32 v50, v50, v11
	global_store_short v1, v50, s[22:23]
	global_store_short_d16_hi v1, v50, s[22:23] offset:1024
	s_add_u32 s22, s22, 0x1a00
	s_addc_u32 s23, s23, 0
	s_waitcnt vmcnt(52)
	v_sub_f32_e32 v52, v124, v96
	v_lshlrev_b32_e32 v50, 16, v192
	v_mul_f32_e32 v52, 0x3fb8aa3b, v52
	v_lshlrev_b32_e32 v51, 16, v193
	v_exp_f32_e32 v53, v52
	v_exp_f32_e64 v54, -v52
	v_mul_f32_e32 v50, 0x3db504f3, v50
	s_nop 0
	v_mul_f32_e32 v50, v53, v50
	v_mul_f32_e32 v12, v54, v51
	v_cvt_pk_bf16_f32 v50, v50, v12
	global_store_short v1, v50, s[22:23]
	global_store_short_d16_hi v1, v50, s[22:23] offset:1024
	s_add_u32 s22, s22, 0x1a00
	s_addc_u32 s23, s23, 0
	s_waitcnt vmcnt(52)
	v_sub_f32_e32 v52, v125, v96
	v_lshlrev_b32_e32 v50, 16, v194
	v_mul_f32_e32 v52, 0x3fb8aa3b, v52
	v_lshlrev_b32_e32 v51, 16, v195
	v_exp_f32_e32 v53, v52
	v_exp_f32_e64 v54, -v52
	v_mul_f32_e32 v50, 0x3db504f3, v50
	s_nop 0
	v_mul_f32_e32 v50, v53, v50
	v_mul_f32_e32 v13, v54, v51
	v_cvt_pk_bf16_f32 v50, v50, v13
	global_store_short v1, v50, s[22:23]
	global_store_short_d16_hi v1, v50, s[22:23] offset:1024
	s_add_u32 s22, s22, 0x1a00
	s_addc_u32 s23, s23, 0
	s_waitcnt vmcnt(52)
	v_sub_f32_e32 v52, v126, v96
	v_lshlrev_b32_e32 v50, 16, v196
	v_mul_f32_e32 v52, 0x3fb8aa3b, v52
	v_lshlrev_b32_e32 v51, 16, v197
	v_exp_f32_e32 v53, v52
	v_exp_f32_e64 v54, -v52
	v_mul_f32_e32 v50, 0x3db504f3, v50
	s_nop 0
	v_mul_f32_e32 v50, v53, v50
	v_mul_f32_e32 v14, v54, v51
	v_cvt_pk_bf16_f32 v50, v50, v14
	global_store_short v1, v50, s[22:23]
	global_store_short_d16_hi v1, v50, s[22:23] offset:1024
	s_add_u32 s22, s22, 0x1a00
	s_addc_u32 s23, s23, 0
	s_waitcnt vmcnt(52)
	v_sub_f32_e32 v52, v127, v96
	v_lshlrev_b32_e32 v50, 16, v198
	v_mul_f32_e32 v52, 0x3fb8aa3b, v52
	v_lshlrev_b32_e32 v51, 16, v199
	v_exp_f32_e32 v53, v52
	v_exp_f32_e64 v54, -v52
	v_mul_f32_e32 v50, 0x3db504f3, v50
	s_nop 0
	v_mul_f32_e32 v50, v53, v50
	v_mul_f32_e32 v15, v54, v51
	v_cvt_pk_bf16_f32 v50, v50, v15
	global_store_short v1, v50, s[22:23]
	global_store_short_d16_hi v1, v50, s[22:23] offset:1024
	s_add_u32 s22, s22, 0x1a00
	s_addc_u32 s23, s23, 0
	v_cvt_pk_bf16_f32 v4, v8, v9
	v_cvt_pk_bf16_f32 v5, v10, v11
	v_cvt_pk_bf16_f32 v6, v12, v13
	v_cvt_pk_bf16_f32 v7, v14, v15
	global_store_dwordx4 v2, v[4:7], s[26:27] offset:112
	v_mul_f32_e32 v50, 0x3fb8aa3b, v96
	v_sub_f32_e32 v51, v127, v96
	v_mul_f32_e32 v52, 0x3fb8aa3b, v127
	v_mul_f32_e32 v51, 0x3fb8aa3b, v51
	v_exp_f32_e32 v50, v50
	v_exp_f32_e32 v51, v51
	v_exp_f32_e32 v52, v52
	s_nop 0
	global_store_dword v0, v50, s[28:29]
	global_store_dword v0, v51, s[28:29] offset:2048
	s_add_u32 s28, s28, 0x1000
	s_addc_u32 s29, s29, 0
	global_store_dword v0, v52, s[28:29]
	s_add_i32 s82, s82, s3
	s_cmpk_lt_i32 s82, 0x100
	s_cbranch_scc1 .Lprep_item
